# conv->in-proj grid barrier elided (no cross-block dependency) and per-tile accumulator zeroing replaced by SrcC=0 MFMAs on the first K-step of each tile
# speedup vs baseline: 1.0059x; 1.0059x over previous
; DI f32x16 zero16() { f32x16 z; for (int i = 0; i < 16; ++i) z[i] = 0.f; return z; }
;     ...
;   f32x16 acc[2][4];
; #pragma unroll
;   for (int i = 0; i < 2; ++i)
; #pragma unroll
;     for (int j = 0; j < 4; ++j) acc[i][j] = zero16();
.LBB0_216:
	v_readlane_b32 s45, v252, 60

; #define MFMA(a, b, c) __builtin_amdgcn_mfma_f32_32x32x16_bf16((a), (b), (c), 0, 0, 0)
;     ...
;   for (int s = 0; s < S; ++s) {
;     G_DMA(s + 1, cur ^ BUFB);
;     {
;       const char* Ab = smem + cur + fA;
;       const char* Bb = smem + cur + fB;
;       __builtin_amdgcn_sched_barrier(0);
; #pragma unroll
;       for (int kk = 0; kk < 4; ++kk) {
;         const int ko = (((kk * 2 + hh) ^ fsw) << 4);
;         bf16x8 af[2], wf[4];
;         af[0] = *(const bf16x8*)(Ab + ko); af[1] = *(const bf16x8*)(Ab + 4096 + ko);
; #pragma unroll
;         for (int ni = 0; ni < 4; ++ni) wf[ni] = *(const bf16x8*)(Bb + ni * 4096 + ko);
; #pragma unroll
;         for (int mi = 0; mi < 2; ++mi)
; #pragma unroll
;           for (int ni = 0; ni < 4; ++ni) acc[mi][ni] = MFMA(wf[ni], af[mi], acc[mi][ni]);
;         if (kk == 1) __builtin_amdgcn_sched_barrier(0);
;       }
;       __builtin_amdgcn_sched_barrier(0);
;     }
.LBB0_218:
	v_add3_u32 v244, s25, v131, v140
	v_add3_u32 v245, s25, v141, v140
	v_add_u32_e32 v187, v245, v144
	v_add_u32_e32 v208, v244, v144
	ds_read_b128 v[188:191], v187 offset:32768
	ds_read_b128 v[204:207], v208
	ds_read_b128 v[192:195], v187 offset:36864
	ds_read_b128 v[196:199], v187 offset:40960
	ds_read_b128 v[200:203], v187 offset:45056
	ds_read_b128 v[216:219], v208 offset:4096
	v_add_u32_e32 v209, v245, v145
	v_add_u32_e32 v215, v244, v145
	ds_read_b128 v[220:223], v209 offset:32768
	ds_read_b128 v[236:239], v215
	ds_read_b128 v[224:227], v209 offset:36864
	ds_read_b128 v[228:231], v209 offset:40960
	ds_read_b128 v[232:235], v209 offset:45056
	ds_read_b128 v[240:243], v215 offset:4096
	s_add_i32 s46, s8, 1
	s_cmp_lt_u32 s46, s58
	s_cselect_b32 s22, s46, s59
	s_lshl_b32 s23, s22, 1
	s_andn2_b32 s23, s23, 31
	s_add_i32 s23, s23, s33
	s_lshr_b32 s23, s23, 3
	s_mov_b32 s9, s25
	s_and_b32 s25, s23, 4
	s_or_b32 s25, s25, s45
	s_and_b32 s23, s23, 0xfffff8
	s_or_b32 s28, s23, s74
	s_lshl_b32 s23, s25, 19
	s_add_u32 s23, s7, s23
	s_addc_u32 s25, s24, 0
	s_lshl_b32 s22, s22, 7
	s_and_b32 s44, s22, 0x780
	s_add_u32 s22, s23, s44
	s_addc_u32 s23, s25, 0
	s_lshl_b32 s40, s28, 8
	s_ashr_i32 s41, s40, 31
	s_lshl_b64 s[40:41], s[40:41], 11
	s_add_u32 s28, s62, s40
	s_addc_u32 s40, s63, s41
	s_xor_b32 s25, s9, 0x10000
	v_add_u32_e32 v128, s25, v142
	v_lshl_add_u64 v[136:137], s[22:23], 0, v[132:133]
	v_readfirstlane_b32 s22, v128
	v_add_u32_e32 v148, 0x2000, v128
	s_mov_b32 m0, s22
	s_mov_b64 s[50:51], 0x20000
	v_readfirstlane_b32 s22, v148
	v_add_u32_e32 v148, 0x4000, v128
	global_load_lds_dwordx4 v[136:137], off
	s_and_b32 s9, s8, 15
	s_cmp_eq_u32 s9, 0
	s_cbranch_scc1 .Lgz_2
	s_waitcnt lgkmcnt(10)
	v_mfma_f32_32x32x16_bf16 v[112:127], v[188:191], v[204:207], v[112:127]
	s_waitcnt lgkmcnt(9)
	v_mfma_f32_32x32x16_bf16 v[96:111], v[192:195], v[204:207], v[96:111]
	v_lshl_add_u64 v[138:139], v[136:137], 0, s[50:51]
	s_mov_b32 m0, s22
	s_mov_b64 s[48:49], 0x40000
	v_readfirstlane_b32 s22, v148
	global_load_lds_dwordx4 v[138:139], off
	s_waitcnt lgkmcnt(8)
	v_mfma_f32_32x32x16_bf16 v[80:95], v[196:199], v[204:207], v[80:95]
	s_waitcnt lgkmcnt(7)
	v_mfma_f32_32x32x16_bf16 v[64:79], v[200:203], v[204:207], v[64:79]
	v_lshl_add_u64 v[138:139], v[136:137], 0, s[48:49]
	s_mov_b32 m0, s22
	s_mov_b64 s[52:53], 0x60000
	global_load_lds_dwordx4 v[138:139], off
	s_waitcnt lgkmcnt(6)
	v_mfma_f32_32x32x16_bf16 v[48:63], v[188:191], v[216:219], v[48:63]
	v_mfma_f32_32x32x16_bf16 v[32:47], v[192:195], v[216:219], v[32:47]
	v_add_u32_e32 v138, 0x6000, v128
	v_lshl_add_u64 v[136:137], v[136:137], 0, s[52:53]
	v_readfirstlane_b32 s22, v138
	s_mov_b32 m0, s22
	s_add_u32 s22, s28, s44
	s_addc_u32 s23, s40, 0
	v_add_u32_e32 v138, 0x8000, v128
	global_load_lds_dwordx4 v[136:137], off
	v_mfma_f32_32x32x16_bf16 v[16:31], v[196:199], v[216:219], v[16:31]
	v_mfma_f32_32x32x16_bf16 v[0:15], v[200:203], v[216:219], v[0:15]
	v_lshl_add_u64 v[136:137], s[22:23], 0, v[132:133]
	v_readfirstlane_b32 s22, v138
	v_add_u32_e32 v148, 0xa000, v128
	s_mov_b32 m0, s22
	v_readfirstlane_b32 s22, v148
	v_add_u32_e32 v148, 0xc000, v128
	global_load_lds_dwordx4 v[136:137], off
	s_branch .Lgj_2
.Lgz_2:
	s_waitcnt lgkmcnt(10)
	v_mfma_f32_32x32x16_bf16 v[112:127], v[188:191], v[204:207], 0
	s_waitcnt lgkmcnt(9)
	v_mfma_f32_32x32x16_bf16 v[96:111], v[192:195], v[204:207], 0
	v_lshl_add_u64 v[138:139], v[136:137], 0, s[50:51]
	s_mov_b32 m0, s22
	s_mov_b64 s[48:49], 0x40000
	v_readfirstlane_b32 s22, v148
	global_load_lds_dwordx4 v[138:139], off
	s_waitcnt lgkmcnt(8)
	v_mfma_f32_32x32x16_bf16 v[80:95], v[196:199], v[204:207], 0
	s_waitcnt lgkmcnt(7)
	v_mfma_f32_32x32x16_bf16 v[64:79], v[200:203], v[204:207], 0
	v_lshl_add_u64 v[138:139], v[136:137], 0, s[48:49]
	s_mov_b32 m0, s22
	s_mov_b64 s[52:53], 0x60000
	global_load_lds_dwordx4 v[138:139], off
	s_waitcnt lgkmcnt(6)
	v_mfma_f32_32x32x16_bf16 v[48:63], v[188:191], v[216:219], 0
	v_mfma_f32_32x32x16_bf16 v[32:47], v[192:195], v[216:219], 0
	v_add_u32_e32 v138, 0x6000, v128
	v_lshl_add_u64 v[136:137], v[136:137], 0, s[52:53]
	v_readfirstlane_b32 s22, v138
	s_mov_b32 m0, s22
	s_add_u32 s22, s28, s44
	s_addc_u32 s23, s40, 0
	v_add_u32_e32 v138, 0x8000, v128
	global_load_lds_dwordx4 v[136:137], off
	v_mfma_f32_32x32x16_bf16 v[16:31], v[196:199], v[216:219], 0
	v_mfma_f32_32x32x16_bf16 v[0:15], v[200:203], v[216:219], 0
	v_lshl_add_u64 v[136:137], s[22:23], 0, v[132:133]
	v_readfirstlane_b32 s22, v138
	v_add_u32_e32 v148, 0xa000, v128
	s_mov_b32 m0, s22
	v_readfirstlane_b32 s22, v148
	v_add_u32_e32 v148, 0xc000, v128
	global_load_lds_dwordx4 v[136:137], off
; #define MFMA(a, b, c) __builtin_amdgcn_mfma_f32_32x32x16_bf16((a), (b), (c), 0, 0, 0)
; DI unsigned pack2(float a, float b) { f32x2_t v = {a, b}; return __builtin_bit_cast(unsigned, __builtin_convertvector(v, bf16x2_t)); }
;     ...
;       for (int kk = 0; kk < 4; ++kk) {
;         const int ko = (((kk * 2 + hh) ^ fsw) << 4);
;         bf16x8 af[2], wf[4];
;         af[0] = *(const bf16x8*)(Ab + ko); af[1] = *(const bf16x8*)(Ab + 4096 + ko);
; #pragma unroll
;         for (int ni = 0; ni < 4; ++ni) wf[ni] = *(const bf16x8*)(Bb + ni * 4096 + ko);
; #pragma unroll
;         for (int mi = 0; mi < 2; ++mi)
; #pragma unroll
;           for (int ni = 0; ni < 4; ++ni) acc[mi][ni] = MFMA(wf[ni], af[mi], acc[mi][ni]);
;         if (kk == 1) __builtin_amdgcn_sched_barrier(0);
;       }
;       __builtin_amdgcn_sched_barrier(0);
;     }
;     asm volatile("s_waitcnt vmcnt(0)" ::: "memory");
;     if ((s & (nk - 1)) == nk - 1) {
;       const int q = slot + (s >> lnk) * nslots;
;       int mt, nt; G_TILEMAP(q, mt, nt);
;       if (dostore) {
; #pragma unroll
;         for (int mi = 0; mi < 2; ++mi) {
;           const size_t m = (size_t)mt * 256 + wm * 64 + mi * 32 + r;
; #pragma unroll
;           for (int ni = 0; ni < 4; ++ni) {
;             __builtin_amdgcn_sched_barrier(0);
;             if (MODE == 0) {
; #pragma unroll
;               for (int gp = 0; gp < 2; ++gp) {
;                 const int g0 = 2 * gp;
;                 uint2 pa, pb;
;                 pa.x = pack2(acc[mi][ni][4 * g0], acc[mi][ni][4 * g0 + 1]); pa.y = pack2(acc[mi][ni][4 * g0 + 2], acc[mi][ni][4 * g0 + 3]);
;                 pb.x = pack2(acc[mi][ni][4 * g0 + 4], acc[mi][ni][4 * g0 + 5]); pb.y = pack2(acc[mi][ni][4 * g0 + 6], acc[mi][ni][4 * g0 + 7]);
;                 { auto rx = __builtin_amdgcn_permlane32_swap(pa.x, pb.x, false, false); pa.x = rx[0]; pb.x = rx[1]; }
;                 { auto ry = __builtin_amdgcn_permlane32_swap(pa.y, pb.y, false, false); pa.y = ry[0]; pb.y = ry[1]; }
;                 const int col = nt * 256 + wn * 128 + ni * 32 + 8 * g0 + 8 * hh;
;                 const uint4 v4 = make_uint4(pa.x, pa.y, pb.x, pb.y);
;                 if (outp != nullptr && nt >= 32) *(uint4*)(outp + m * 2048 + (col - 8192)) = v4;
;                 else if (col < nvalid) *(uint4*)(C + m * ldc + col) = v4;
.Lgj_2:
	v_add_u32_e32 v187, v245, v146
	v_add_u32_e32 v208, v244, v146
	ds_read_b128 v[188:191], v187 offset:32768
	ds_read_b128 v[204:207], v208
	ds_read_b128 v[192:195], v187 offset:36864
	ds_read_b128 v[196:199], v187 offset:40960
	ds_read_b128 v[200:203], v187 offset:45056
	ds_read_b128 v[216:219], v208 offset:4096
	s_waitcnt lgkmcnt(10)
	v_mfma_f32_32x32x16_bf16 v[112:127], v[220:223], v[236:239], v[112:127]
	s_waitcnt lgkmcnt(9)
	v_mfma_f32_32x32x16_bf16 v[96:111], v[224:227], v[236:239], v[96:111]
	v_lshl_add_u64 v[138:139], v[136:137], 0, s[50:51]
	s_mov_b32 m0, s22
	v_readfirstlane_b32 s22, v148
	v_add_u32_e32 v128, 0xe000, v128
	global_load_lds_dwordx4 v[138:139], off
	s_waitcnt lgkmcnt(8)
	v_mfma_f32_32x32x16_bf16 v[80:95], v[228:231], v[236:239], v[80:95]
	s_waitcnt lgkmcnt(7)
	v_mfma_f32_32x32x16_bf16 v[64:79], v[232:235], v[236:239], v[64:79]
	v_lshl_add_u64 v[138:139], v[136:137], 0, s[48:49]
	s_mov_b32 m0, s22
	v_readfirstlane_b32 s22, v128
	global_load_lds_dwordx4 v[138:139], off
	s_waitcnt lgkmcnt(6)
	v_mfma_f32_32x32x16_bf16 v[48:63], v[220:223], v[240:243], v[48:63]
	v_mfma_f32_32x32x16_bf16 v[32:47], v[224:227], v[240:243], v[32:47]
	v_lshl_add_u64 v[136:137], v[136:137], 0, s[52:53]
	s_mov_b32 m0, s22
	s_add_i32 s9, s9, 0
	global_load_lds_dwordx4 v[136:137], off
	v_mfma_f32_32x32x16_bf16 v[16:31], v[228:231], v[240:243], v[16:31]
	v_mfma_f32_32x32x16_bf16 v[0:15], v[232:235], v[240:243], v[0:15]
	v_add_u32_e32 v209, v245, v147
	v_add_u32_e32 v215, v244, v147
	ds_read_b128 v[220:223], v209 offset:32768
	ds_read_b128 v[236:239], v215
	ds_read_b128 v[224:227], v209 offset:36864
	ds_read_b128 v[228:231], v209 offset:40960
	ds_read_b128 v[232:235], v209 offset:45056
	ds_read_b128 v[240:243], v215 offset:4096
	s_waitcnt lgkmcnt(10)
	v_mfma_f32_32x32x16_bf16 v[112:127], v[188:191], v[204:207], v[112:127]
	s_waitcnt lgkmcnt(9)
	v_mfma_f32_32x32x16_bf16 v[96:111], v[192:195], v[204:207], v[96:111]
	s_waitcnt lgkmcnt(8)
	v_mfma_f32_32x32x16_bf16 v[80:95], v[196:199], v[204:207], v[80:95]
	s_waitcnt lgkmcnt(7)
	v_mfma_f32_32x32x16_bf16 v[64:79], v[200:203], v[204:207], v[64:79]
	s_waitcnt lgkmcnt(6)
	v_mfma_f32_32x32x16_bf16 v[48:63], v[188:191], v[216:219], v[48:63]
	v_mfma_f32_32x32x16_bf16 v[32:47], v[192:195], v[216:219], v[32:47]
	v_mfma_f32_32x32x16_bf16 v[16:31], v[196:199], v[216:219], v[16:31]
	v_mfma_f32_32x32x16_bf16 v[0:15], v[200:203], v[216:219], v[0:15]
	s_waitcnt lgkmcnt(4)
	v_mfma_f32_32x32x16_bf16 v[112:127], v[220:223], v[236:239], v[112:127]
	s_waitcnt lgkmcnt(3)
	v_mfma_f32_32x32x16_bf16 v[96:111], v[224:227], v[236:239], v[96:111]
	s_waitcnt lgkmcnt(2)
	v_mfma_f32_32x32x16_bf16 v[80:95], v[228:231], v[236:239], v[80:95]
	s_waitcnt lgkmcnt(1)
	v_mfma_f32_32x32x16_bf16 v[64:79], v[232:235], v[236:239], v[64:79]
	s_waitcnt lgkmcnt(0)
	v_mfma_f32_32x32x16_bf16 v[48:63], v[220:223], v[240:243], v[48:63]
	v_mfma_f32_32x32x16_bf16 v[32:47], v[224:227], v[240:243], v[32:47]
	v_mfma_f32_32x32x16_bf16 v[16:31], v[228:231], v[240:243], v[16:31]
	v_mfma_f32_32x32x16_bf16 v[0:15], v[232:235], v[240:243], v[0:15]
	s_waitcnt vmcnt(0)
	s_and_b32 s9, s8, 15
	s_cmp_lg_u32 s9, 15
	s_cbranch_scc1 .LBB0_217
	s_lshl_b32 s8, s8, 1
	s_and_b32 s8, s8, 0x7fffffe0
	s_add_i32 s8, s8, s33
	s_lshr_b32 s9, s8, 3
	s_and_b32 s22, s9, 4
	s_or_b32 s22, s22, s45
	s_and_b32 s9, s9, 0xfffff8
	s_or_b32 s9, s9, s74
	s_lshl_b32 s28, s22, 8
	v_lshl_add_u64 v[136:137], v[134:135], 0, s[28:29]
	s_lshl_b32 s28, s9, 8
	s_cmpk_lt_u32 s8, 0x100
	s_cselect_b64 s[8:9], -1, 0
	s_xor_b64 s[22:23], s[56:57], -1
	v_lshlrev_b64 v[138:139], 14, v[136:137]
	v_or_b32_e32 v128, s28, v143
	s_mov_b64 s[40:41], -1
	s_or_b64 s[44:45], s[22:23], s[8:9]
	v_lshl_add_u64 v[138:139], s[30:31], 0, v[138:139]
	v_cvt_pk_bf16_f32 v112, v112, v113
	v_cvt_pk_bf16_f32 v113, v114, v115
	v_cvt_pk_bf16_f32 v114, v116, v117
	v_cvt_pk_bf16_f32 v115, v118, v119
	s_nop 0
	v_permlane32_swap_b32_e32 v112, v114
	v_permlane32_swap_b32_e32 v113, v115
	s_and_b64 vcc, exec, s[44:45]
	s_cbranch_vccz .LBB0_223
	s_cmp_gt_u32 s28, 0x3fffffff
	s_cbranch_scc1 .LBB0_222
	v_lshl_add_u64 v[116:117], v[128:129], 1, v[138:139]
	global_store_dwordx4 v[116:117], v[112:115], off

; #define MFMA(a, b, c) __builtin_amdgcn_mfma_f32_32x32x16_bf16((a), (b), (c), 0, 0, 0)
; DI f32x16 zero16() { f32x16 z; for (int i = 0; i < 16; ++i) z[i] = 0.f; return z; }
;     ...
;   for (int s = 0; s < S; ++s) {
;     G_DMA(s + 1, cur ^ BUFB);
;     {
;       const char* Ab = smem + cur + fA;
;       const char* Bb = smem + cur + fB;
;       __builtin_amdgcn_sched_barrier(0);
; #pragma unroll
;       for (int kk = 0; kk < 4; ++kk) {
;         const int ko = (((kk * 2 + hh) ^ fsw) << 4);
;         bf16x8 af[2], wf[4];
;         af[0] = *(const bf16x8*)(Ab + ko); af[1] = *(const bf16x8*)(Ab + 4096 + ko);
; #pragma unroll
;         for (int ni = 0; ni < 4; ++ni) wf[ni] = *(const bf16x8*)(Bb + ni * 4096 + ko);
; #pragma unroll
;         for (int mi = 0; mi < 2; ++mi)
; #pragma unroll
;           for (int ni = 0; ni < 4; ++ni) acc[mi][ni] = MFMA(wf[ni], af[mi], acc[mi][ni]);
;         if (kk == 1) __builtin_amdgcn_sched_barrier(0);
;       }
;       __builtin_amdgcn_sched_barrier(0);
;     }
;     ...
; #pragma unroll
;       for (int i = 0; i < 2; ++i)
; #pragma unroll
;         for (int j = 0; j < 4; ++j) acc[i][j] = zero16();
;     }
;     asm volatile("s_waitcnt lgkmcnt(0)" ::: "memory"); __builtin_amdgcn_s_barrier(); asm volatile("" ::: "memory");
.LBB0_739:
	s_or_b64 exec, exec, s[22:23]
.LBB0_740:
	s_waitcnt lgkmcnt(0)
	s_barrier
	v_readlane_b32 s22, v251, 35
	s_cmp_eq_u32 s7, s22
	s_mov_b32 s8, s7
	s_cbranch_scc1 .LBB0_774
.LBB0_741:
	v_add3_u32 v187, s6, v131, v140
	v_add3_u32 v208, s6, v141, v140
	v_add_u32_e32 v182, v208, v144
	v_add_u32_e32 v183, v187, v144
	ds_read_b128 v[192:195], v182 offset:32768
	ds_read_b128 v[216:219], v183
	ds_read_b128 v[196:199], v182 offset:36864
	ds_read_b128 v[200:203], v182 offset:40960
	ds_read_b128 v[204:207], v182 offset:45056
	ds_read_b128 v[220:223], v183 offset:4096
	v_add_u32_e32 v184, v208, v145
	v_add_u32_e32 v185, v187, v145
	ds_read_b128 v[224:227], v184 offset:32768
	ds_read_b128 v[240:243], v185
	ds_read_b128 v[228:231], v184 offset:36864
	ds_read_b128 v[232:235], v184 offset:40960
	ds_read_b128 v[236:239], v184 offset:45056
	ds_read_b128 v[244:247], v185 offset:4096
	s_add_i32 s7, s8, 1
	s_mov_b32 s9, s6
	s_cmp_lt_u32 s7, s22
	v_readlane_b32 s6, v251, 36
	s_cselect_b32 s24, s7, s6
	s_lshl_b32 s6, s24, 1
	s_and_b32 s6, s6, 0x7ffffe0
	s_add_i32 s6, s6, s33
	s_lshl_b32 s6, s6, 5
	s_and_b32 s22, s6, 0xffffff00
	s_ashr_i32 s23, s22, 31
	s_lshl_b64 s[22:23], s[22:23], 11
	s_add_u32 s22, s62, s22
	s_addc_u32 s23, s63, s23
	s_xor_b32 s6, s9, 0x10000
	v_add_u32_e32 v128, s6, v142
	s_lshl_b32 s24, s24, 7
	s_and_b32 s28, s24, 0x780
	v_readfirstlane_b32 s24, v128
	v_add_u32_e32 v152, 0x2000, v128
	v_lshl_add_u64 v[148:149], v[134:135], 0, s[28:29]
	s_mov_b32 m0, s24
	s_mov_b64 s[44:45], 0x20000
	v_readfirstlane_b32 s24, v152
	v_add_u32_e32 v152, 0x4000, v128
	global_load_lds_dwordx4 v[148:149], off
	s_and_b32 s9, s8, 15
	s_cmp_eq_u32 s9, 0
	s_cbranch_scc1 .Lgz_5
	s_waitcnt lgkmcnt(10)
	v_mfma_f32_32x32x16_bf16 v[112:127], v[192:195], v[216:219], v[112:127]
	s_waitcnt lgkmcnt(9)
	v_mfma_f32_32x32x16_bf16 v[96:111], v[196:199], v[216:219], v[96:111]
	v_lshl_add_u64 v[150:151], v[148:149], 0, s[44:45]
	s_mov_b32 m0, s24
	s_mov_b64 s[42:43], 0x40000
	v_readfirstlane_b32 s24, v152
	global_load_lds_dwordx4 v[150:151], off
	s_waitcnt lgkmcnt(8)
	v_mfma_f32_32x32x16_bf16 v[80:95], v[200:203], v[216:219], v[80:95]
	s_waitcnt lgkmcnt(7)
	v_mfma_f32_32x32x16_bf16 v[64:79], v[204:207], v[216:219], v[64:79]
	v_lshl_add_u64 v[150:151], v[148:149], 0, s[42:43]
	s_mov_b32 m0, s24
	s_mov_b64 s[46:47], 0x60000
	global_load_lds_dwordx4 v[150:151], off
	s_waitcnt lgkmcnt(6)
	v_mfma_f32_32x32x16_bf16 v[48:63], v[192:195], v[220:223], v[48:63]
	v_mfma_f32_32x32x16_bf16 v[32:47], v[196:199], v[220:223], v[32:47]
	v_add_u32_e32 v150, 0x6000, v128
	s_add_u32 s22, s22, s28
	v_readfirstlane_b32 s24, v150
	v_lshl_add_u64 v[148:149], v[148:149], 0, s[46:47]
	s_mov_b32 m0, s24
	s_addc_u32 s23, s23, 0
	v_add_u32_e32 v150, 0x8000, v128
	global_load_lds_dwordx4 v[148:149], off
	v_mfma_f32_32x32x16_bf16 v[16:31], v[200:203], v[220:223], v[16:31]
	v_mfma_f32_32x32x16_bf16 v[0:15], v[204:207], v[220:223], v[0:15]
	v_lshl_add_u64 v[148:149], s[22:23], 0, v[132:133]
	v_readfirstlane_b32 s22, v150
	v_add_u32_e32 v152, 0xa000, v128
	s_mov_b32 m0, s22
	v_readfirstlane_b32 s22, v152
	v_add_u32_e32 v152, 0xc000, v128
	global_load_lds_dwordx4 v[148:149], off
	s_branch .Lgj_5
.Lgz_5:
	s_waitcnt lgkmcnt(10)
	v_mfma_f32_32x32x16_bf16 v[112:127], v[192:195], v[216:219], 0
	s_waitcnt lgkmcnt(9)
	v_mfma_f32_32x32x16_bf16 v[96:111], v[196:199], v[216:219], 0
	v_lshl_add_u64 v[150:151], v[148:149], 0, s[44:45]
	s_mov_b32 m0, s24
	s_mov_b64 s[42:43], 0x40000
	v_readfirstlane_b32 s24, v152
	global_load_lds_dwordx4 v[150:151], off
	s_waitcnt lgkmcnt(8)
	v_mfma_f32_32x32x16_bf16 v[80:95], v[200:203], v[216:219], 0
	s_waitcnt lgkmcnt(7)
	v_mfma_f32_32x32x16_bf16 v[64:79], v[204:207], v[216:219], 0
	v_lshl_add_u64 v[150:151], v[148:149], 0, s[42:43]
	s_mov_b32 m0, s24
	s_mov_b64 s[46:47], 0x60000
	global_load_lds_dwordx4 v[150:151], off
	s_waitcnt lgkmcnt(6)
	v_mfma_f32_32x32x16_bf16 v[48:63], v[192:195], v[220:223], 0
	v_mfma_f32_32x32x16_bf16 v[32:47], v[196:199], v[220:223], 0
	v_add_u32_e32 v150, 0x6000, v128
	s_add_u32 s22, s22, s28
	v_readfirstlane_b32 s24, v150
	v_lshl_add_u64 v[148:149], v[148:149], 0, s[46:47]
	s_mov_b32 m0, s24
	s_addc_u32 s23, s23, 0
	v_add_u32_e32 v150, 0x8000, v128
	global_load_lds_dwordx4 v[148:149], off
	v_mfma_f32_32x32x16_bf16 v[16:31], v[200:203], v[220:223], 0
	v_mfma_f32_32x32x16_bf16 v[0:15], v[204:207], v[220:223], 0
	v_lshl_add_u64 v[148:149], s[22:23], 0, v[132:133]
	v_readfirstlane_b32 s22, v150
	v_add_u32_e32 v152, 0xa000, v128
	s_mov_b32 m0, s22
	v_readfirstlane_b32 s22, v152
	v_add_u32_e32 v152, 0xc000, v128
	global_load_lds_dwordx4 v[148:149], off
; #define MFMA(a, b, c) __builtin_amdgcn_mfma_f32_32x32x16_bf16((a), (b), (c), 0, 0, 0)
; DI unsigned pack2(float a, float b) { f32x2_t v = {a, b}; return __builtin_bit_cast(unsigned, __builtin_convertvector(v, bf16x2_t)); }
;     ...
;       for (int kk = 0; kk < 4; ++kk) {
;         const int ko = (((kk * 2 + hh) ^ fsw) << 4);
;         bf16x8 af[2], wf[4];
;         af[0] = *(const bf16x8*)(Ab + ko); af[1] = *(const bf16x8*)(Ab + 4096 + ko);
; #pragma unroll
;         for (int ni = 0; ni < 4; ++ni) wf[ni] = *(const bf16x8*)(Bb + ni * 4096 + ko);
; #pragma unroll
;         for (int mi = 0; mi < 2; ++mi)
; #pragma unroll
;           for (int ni = 0; ni < 4; ++ni) acc[mi][ni] = MFMA(wf[ni], af[mi], acc[mi][ni]);
;         if (kk == 1) __builtin_amdgcn_sched_barrier(0);
;       }
;       __builtin_amdgcn_sched_barrier(0);
;     }
;     asm volatile("s_waitcnt vmcnt(0)" ::: "memory");
;     if ((s & (nk - 1)) == nk - 1) {
;       const int q = slot + (s >> lnk) * nslots;
;       int mt, nt; G_TILEMAP(q, mt, nt);
;       if (dostore) {
; #pragma unroll
;         for (int mi = 0; mi < 2; ++mi) {
;           const size_t m = (size_t)mt * 256 + wm * 64 + mi * 32 + r;
; #pragma unroll
;           for (int ni = 0; ni < 4; ++ni) {
;             __builtin_amdgcn_sched_barrier(0);
;             if (MODE == 0) {
; #pragma unroll
;               for (int gp = 0; gp < 2; ++gp) {
;                 const int g0 = 2 * gp;
;                 uint2 pa, pb;
;                 pa.x = pack2(acc[mi][ni][4 * g0], acc[mi][ni][4 * g0 + 1]); pa.y = pack2(acc[mi][ni][4 * g0 + 2], acc[mi][ni][4 * g0 + 3]);
;                 pb.x = pack2(acc[mi][ni][4 * g0 + 4], acc[mi][ni][4 * g0 + 5]); pb.y = pack2(acc[mi][ni][4 * g0 + 6], acc[mi][ni][4 * g0 + 7]);
;                 { auto rx = __builtin_amdgcn_permlane32_swap(pa.x, pb.x, false, false); pa.x = rx[0]; pb.x = rx[1]; }
;                 { auto ry = __builtin_amdgcn_permlane32_swap(pa.y, pb.y, false, false); pa.y = ry[0]; pb.y = ry[1]; }
;                 const int col = nt * 256 + wn * 128 + ni * 32 + 8 * g0 + 8 * hh;
;                 const uint4 v4 = make_uint4(pa.x, pa.y, pb.x, pb.y);
;                 if (outp != nullptr && nt >= 32) *(uint4*)(outp + m * 2048 + (col - 8192)) = v4;
;                 else if (col < nvalid) *(uint4*)(C + m * ldc + col) = v4;
.Lgj_5:
	v_add_u32_e32 v182, v208, v146
	v_add_u32_e32 v183, v187, v146
	ds_read_b128 v[192:195], v182 offset:32768
	ds_read_b128 v[216:219], v183
	ds_read_b128 v[196:199], v182 offset:36864
	ds_read_b128 v[200:203], v182 offset:40960
	ds_read_b128 v[204:207], v182 offset:45056
	ds_read_b128 v[220:223], v183 offset:4096
	s_waitcnt lgkmcnt(10)
	v_mfma_f32_32x32x16_bf16 v[112:127], v[224:227], v[240:243], v[112:127]
	s_waitcnt lgkmcnt(9)
	v_mfma_f32_32x32x16_bf16 v[96:111], v[228:231], v[240:243], v[96:111]
	v_lshl_add_u64 v[150:151], v[148:149], 0, s[44:45]
	s_mov_b32 m0, s22
	v_readfirstlane_b32 s22, v152
	v_add_u32_e32 v128, 0xe000, v128
	global_load_lds_dwordx4 v[150:151], off
	s_waitcnt lgkmcnt(8)
	v_mfma_f32_32x32x16_bf16 v[80:95], v[232:235], v[240:243], v[80:95]
	s_waitcnt lgkmcnt(7)
	v_mfma_f32_32x32x16_bf16 v[64:79], v[236:239], v[240:243], v[64:79]
	v_lshl_add_u64 v[150:151], v[148:149], 0, s[42:43]
	s_mov_b32 m0, s22
	v_readfirstlane_b32 s22, v128
	global_load_lds_dwordx4 v[150:151], off
	s_waitcnt lgkmcnt(6)
	v_mfma_f32_32x32x16_bf16 v[48:63], v[224:227], v[244:247], v[48:63]
	v_mfma_f32_32x32x16_bf16 v[32:47], v[228:231], v[244:247], v[32:47]
	v_lshl_add_u64 v[148:149], v[148:149], 0, s[46:47]
	s_mov_b32 m0, s22
	s_add_i32 s9, s9, 0
	global_load_lds_dwordx4 v[148:149], off
	v_mfma_f32_32x32x16_bf16 v[16:31], v[232:235], v[244:247], v[16:31]
	v_mfma_f32_32x32x16_bf16 v[0:15], v[236:239], v[244:247], v[0:15]
	v_add_u32_e32 v184, v208, v147
	v_add_u32_e32 v185, v187, v147
	ds_read_b128 v[224:227], v184 offset:32768
	ds_read_b128 v[240:243], v185
	ds_read_b128 v[228:231], v184 offset:36864
	ds_read_b128 v[232:235], v184 offset:40960
	ds_read_b128 v[236:239], v184 offset:45056
	ds_read_b128 v[244:247], v185 offset:4096
	s_waitcnt lgkmcnt(10)
	v_mfma_f32_32x32x16_bf16 v[112:127], v[192:195], v[216:219], v[112:127]
	s_waitcnt lgkmcnt(9)
	v_mfma_f32_32x32x16_bf16 v[96:111], v[196:199], v[216:219], v[96:111]
	s_waitcnt lgkmcnt(8)
	v_mfma_f32_32x32x16_bf16 v[80:95], v[200:203], v[216:219], v[80:95]
	s_waitcnt lgkmcnt(7)
	v_mfma_f32_32x32x16_bf16 v[64:79], v[204:207], v[216:219], v[64:79]
	s_waitcnt lgkmcnt(6)
	v_mfma_f32_32x32x16_bf16 v[48:63], v[192:195], v[220:223], v[48:63]
	v_mfma_f32_32x32x16_bf16 v[32:47], v[196:199], v[220:223], v[32:47]
	v_mfma_f32_32x32x16_bf16 v[16:31], v[200:203], v[220:223], v[16:31]
	v_mfma_f32_32x32x16_bf16 v[0:15], v[204:207], v[220:223], v[0:15]
	s_waitcnt lgkmcnt(4)
	v_mfma_f32_32x32x16_bf16 v[112:127], v[224:227], v[240:243], v[112:127]
	s_waitcnt lgkmcnt(3)
	v_mfma_f32_32x32x16_bf16 v[96:111], v[228:231], v[240:243], v[96:111]
	s_waitcnt lgkmcnt(2)
	v_mfma_f32_32x32x16_bf16 v[80:95], v[232:235], v[240:243], v[80:95]
	s_waitcnt lgkmcnt(1)
	v_mfma_f32_32x32x16_bf16 v[64:79], v[236:239], v[240:243], v[64:79]
	s_waitcnt lgkmcnt(0)
	v_mfma_f32_32x32x16_bf16 v[48:63], v[224:227], v[244:247], v[48:63]
	v_mfma_f32_32x32x16_bf16 v[32:47], v[228:231], v[244:247], v[32:47]
	v_mfma_f32_32x32x16_bf16 v[16:31], v[232:235], v[244:247], v[16:31]
	v_mfma_f32_32x32x16_bf16 v[0:15], v[236:239], v[244:247], v[0:15]
	s_waitcnt vmcnt(0)
	s_and_b32 s9, s8, 15
	s_cmp_lg_u32 s9, 15
	s_cbranch_scc1 .LBB0_740
	s_lshl_b32 s8, s8, 1
	s_and_b32 s8, s8, 0x3ffffe0
	s_add_i32 s8, s8, s33
	s_lshl_b32 s8, s8, 5
	s_and_b32 s8, s8, 0x7fffff00
	v_or_b32_e32 v148, s8, v143
	v_cvt_pk_bf16_f32 v112, v112, v113
	v_cvt_pk_bf16_f32 v113, v114, v115
	v_cvt_pk_bf16_f32 v114, v116, v117
	v_cvt_pk_bf16_f32 v115, v118, v119
	s_movk_i32 s8, 0x1480
	v_permlane32_swap_b32_e32 v112, v114
	v_permlane32_swap_b32_e32 v113, v115
	v_cmp_gt_u32_e32 vcc, s8, v148
	v_lshlrev_b32_e32 v128, 1, v148
	s_and_saveexec_b64 s[22:23], vcc
	s_cbranch_execz .LBB0_744
	v_lshl_add_u64 v[116:117], v[136:137], 0, v[128:129]
	global_store_dwordx4 v[116:117], v[112:115], off

; #define MFMA(a, b, c) __builtin_amdgcn_mfma_f32_32x32x16_bf16((a), (b), (c), 0, 0, 0)
;     ...
;   for (int s = 0; s < S; ++s) {
;     G_DMA(s + 1, cur ^ BUFB);
;     {
;       const char* Ab = smem + cur + fA;
;       const char* Bb = smem + cur + fB;
;       __builtin_amdgcn_sched_barrier(0);
; #pragma unroll
;       for (int kk = 0; kk < 4; ++kk) {
;         const int ko = (((kk * 2 + hh) ^ fsw) << 4);
;         bf16x8 af[2], wf[4];
;         af[0] = *(const bf16x8*)(Ab + ko); af[1] = *(const bf16x8*)(Ab + 4096 + ko);
; #pragma unroll
;         for (int ni = 0; ni < 4; ++ni) wf[ni] = *(const bf16x8*)(Bb + ni * 4096 + ko);
; #pragma unroll
;         for (int mi = 0; mi < 2; ++mi)
; #pragma unroll
;           for (int ni = 0; ni < 4; ++ni) acc[mi][ni] = MFMA(wf[ni], af[mi], acc[mi][ni]);
;         if (kk == 1) __builtin_amdgcn_sched_barrier(0);
;       }
;       __builtin_amdgcn_sched_barrier(0);
;     }
.LBB0_1108:
	v_add3_u32 v215, s6, v187, v189
	v_add3_u32 v244, s6, v188, v189
	v_add_u32_e32 v182, v244, v190
	v_add_u32_e32 v183, v215, v190
	ds_read_b128 v[170:173], v182 offset:32768
	ds_read_b128 v[194:197], v183
	ds_read_b128 v[198:201], v182 offset:36864
	ds_read_b128 v[202:205], v182 offset:40960
	ds_read_b128 v[206:209], v182 offset:45056
	ds_read_b128 v[216:219], v183 offset:4096
	v_add_u32_e32 v184, v244, v191
	v_add_u32_e32 v185, v215, v191
	ds_read_b128 v[220:223], v184 offset:32768
	ds_read_b128 v[236:239], v185
	ds_read_b128 v[224:227], v184 offset:36864
	ds_read_b128 v[228:231], v184 offset:40960
	ds_read_b128 v[232:235], v184 offset:45056
	ds_read_b128 v[240:243], v185 offset:4096
	s_add_i32 s7, s8, 1
	s_mov_b32 s9, s6
	s_cmp_lt_u32 s7, s60
	v_readlane_b32 s6, v253, 59
	s_cselect_b32 s6, s7, s6
	s_lshl_b32 s22, s6, 1
	s_andn2_b32 s22, s22, 31
	s_add_i32 s22, s22, s33
	s_lshr_b32 s23, s22, 4
	s_lshr_b32 s22, s22, 3
	s_and_b32 s22, s22, 12
	v_readlane_b32 s46, v252, 41
	s_and_b32 s23, s23, 0xfffff8
	s_or_b32 s22, s22, s46
	s_or_b32 s24, s23, s74
	s_lshl_b32 s22, s22, 19
	v_readlane_b32 s40, v253, 39
	v_readlane_b32 s41, v253, 40
	s_add_u32 s22, s40, s22
	s_addc_u32 s23, s41, 0
	s_lshl_b32 s6, s6, 7
	s_and_b32 s28, s6, 0x780
	s_add_u32 s22, s22, s28
	s_addc_u32 s23, s23, 0
	s_lshl_b32 s24, s24, 8
	s_ashr_i32 s25, s24, 31
	s_lshl_b64 s[24:25], s[24:25], 11
	s_add_u32 s24, s62, s24
	s_addc_u32 s25, s63, s25
	s_xor_b32 s6, s9, 0x10000
	v_add_u32_e32 v245, s6, v131
	v_lshl_add_u64 v[246:247], s[22:23], 0, v[132:133]
	v_readfirstlane_b32 s22, v245
	v_add_u32_e32 v250, 0x2000, v245
	s_mov_b32 m0, s22
	s_mov_b64 s[42:43], 0x20000
	v_readfirstlane_b32 s22, v250
	v_add_u32_e32 v250, 0x4000, v245
	global_load_lds_dwordx4 v[246:247], off
	s_and_b32 s9, s8, 15
	s_cmp_eq_u32 s9, 0
	s_cbranch_scc1 .Lgz_6
	s_waitcnt lgkmcnt(10)
	v_mfma_f32_32x32x16_bf16 v[112:127], v[170:173], v[194:197], v[112:127]
	s_waitcnt lgkmcnt(9)
	v_mfma_f32_32x32x16_bf16 v[96:111], v[198:201], v[194:197], v[96:111]
	v_lshl_add_u64 v[248:249], v[246:247], 0, s[42:43]
	s_mov_b32 m0, s22
	s_mov_b64 s[40:41], 0x40000
	v_readfirstlane_b32 s22, v250
	v_add_u32_e32 v250, 0x6000, v245
	global_load_lds_dwordx4 v[248:249], off
	s_waitcnt lgkmcnt(8)
	v_mfma_f32_32x32x16_bf16 v[80:95], v[202:205], v[194:197], v[80:95]
	s_waitcnt lgkmcnt(7)
	v_mfma_f32_32x32x16_bf16 v[64:79], v[206:209], v[194:197], v[64:79]
	v_lshl_add_u64 v[248:249], v[246:247], 0, s[40:41]
	s_mov_b32 m0, s22
	v_readfirstlane_b32 s22, v250
	global_load_lds_dwordx4 v[248:249], off
	s_waitcnt lgkmcnt(6)
	v_mfma_f32_32x32x16_bf16 v[48:63], v[170:173], v[216:219], v[48:63]
	v_mfma_f32_32x32x16_bf16 v[32:47], v[198:201], v[216:219], v[32:47]
	s_mov_b64 s[44:45], 0x60000
	s_mov_b32 m0, s22
	s_add_u32 s22, s24, s28
	v_lshl_add_u64 v[246:247], v[246:247], 0, s[44:45]
	s_addc_u32 s23, s25, 0
	v_add_u32_e32 v250, 0x8000, v245
	global_load_lds_dwordx4 v[246:247], off
	v_mfma_f32_32x32x16_bf16 v[16:31], v[202:205], v[216:219], v[16:31]
	v_mfma_f32_32x32x16_bf16 v[0:15], v[206:209], v[216:219], v[0:15]
	v_lshl_add_u64 v[246:247], s[22:23], 0, v[132:133]
	v_readfirstlane_b32 s22, v250
	v_add_u32_e32 v250, 0xa000, v245
	s_mov_b32 m0, s22
	v_readfirstlane_b32 s22, v250
	v_add_u32_e32 v250, 0xc000, v245
	global_load_lds_dwordx4 v[246:247], off
	s_branch .Lgj_6
.Lgz_6:
	s_waitcnt lgkmcnt(10)
	v_mfma_f32_32x32x16_bf16 v[112:127], v[170:173], v[194:197], 0
	s_waitcnt lgkmcnt(9)
	v_mfma_f32_32x32x16_bf16 v[96:111], v[198:201], v[194:197], 0
	v_lshl_add_u64 v[248:249], v[246:247], 0, s[42:43]
	s_mov_b32 m0, s22
	s_mov_b64 s[40:41], 0x40000
	v_readfirstlane_b32 s22, v250
	v_add_u32_e32 v250, 0x6000, v245
	global_load_lds_dwordx4 v[248:249], off
	s_waitcnt lgkmcnt(8)
	v_mfma_f32_32x32x16_bf16 v[80:95], v[202:205], v[194:197], 0
	s_waitcnt lgkmcnt(7)
	v_mfma_f32_32x32x16_bf16 v[64:79], v[206:209], v[194:197], 0
	v_lshl_add_u64 v[248:249], v[246:247], 0, s[40:41]
	s_mov_b32 m0, s22
	v_readfirstlane_b32 s22, v250
	global_load_lds_dwordx4 v[248:249], off
	s_waitcnt lgkmcnt(6)
	v_mfma_f32_32x32x16_bf16 v[48:63], v[170:173], v[216:219], 0
	v_mfma_f32_32x32x16_bf16 v[32:47], v[198:201], v[216:219], 0
	s_mov_b64 s[44:45], 0x60000
	s_mov_b32 m0, s22
	s_add_u32 s22, s24, s28
	v_lshl_add_u64 v[246:247], v[246:247], 0, s[44:45]
	s_addc_u32 s23, s25, 0
	v_add_u32_e32 v250, 0x8000, v245
	global_load_lds_dwordx4 v[246:247], off
	v_mfma_f32_32x32x16_bf16 v[16:31], v[202:205], v[216:219], 0
	v_mfma_f32_32x32x16_bf16 v[0:15], v[206:209], v[216:219], 0
	v_lshl_add_u64 v[246:247], s[22:23], 0, v[132:133]
	v_readfirstlane_b32 s22, v250
	v_add_u32_e32 v250, 0xa000, v245
	s_mov_b32 m0, s22
	v_readfirstlane_b32 s22, v250
	v_add_u32_e32 v250, 0xc000, v245
	global_load_lds_dwordx4 v[246:247], off
; #define MFMA(a, b, c) __builtin_amdgcn_mfma_f32_32x32x16_bf16((a), (b), (c), 0, 0, 0)
; DI unsigned pack2(float a, float b) { f32x2_t v = {a, b}; return __builtin_bit_cast(unsigned, __builtin_convertvector(v, bf16x2_t)); }
;     ...
;       for (int kk = 0; kk < 4; ++kk) {
;         const int ko = (((kk * 2 + hh) ^ fsw) << 4);
;         bf16x8 af[2], wf[4];
;         af[0] = *(const bf16x8*)(Ab + ko); af[1] = *(const bf16x8*)(Ab + 4096 + ko);
; #pragma unroll
;         for (int ni = 0; ni < 4; ++ni) wf[ni] = *(const bf16x8*)(Bb + ni * 4096 + ko);
; #pragma unroll
;         for (int mi = 0; mi < 2; ++mi)
; #pragma unroll
;           for (int ni = 0; ni < 4; ++ni) acc[mi][ni] = MFMA(wf[ni], af[mi], acc[mi][ni]);
;         if (kk == 1) __builtin_amdgcn_sched_barrier(0);
;       }
;       __builtin_amdgcn_sched_barrier(0);
;     }
;     asm volatile("s_waitcnt vmcnt(0)" ::: "memory");
;     ...
;             for (int g = 0; g < 4; ++g) {
;               const int n = nt * 256 + wn * 128 + ni * 32 + 8 * g + 4 * hh;
;               const float a0 = acc[mi][ni][4 * g], a1 = acc[mi][ni][4 * g + 1], a2 = acc[mi][ni][4 * g + 2], a3 = acc[mi][ni][4 * g + 3];
;               if (MODE == 0) {
;                 uint2 pk; pk.x = pack2(a0, a1); pk.y = pack2(a2, a3);
;                 if (outp != nullptr && nt >= 32) *(uint2*)(outp + m * 2048 + (n - 8192)) = pk;
;                 else if (n < nvalid) *(uint2*)(C + m * ldc + n) = pk;
;               } else if (MODE == 2) {
;                 const unsigned p01 = pack2(a0, a1), p23 = pack2(a2, a3);
;                 bf16_t* dst = ((nt < 8) ? C : outp) + ((size_t)(n & 2047) * 8 + (m >> 12)) * SEQ + (m & 4095);
;                 dst[0] = (bf16_t)(p01 & 0xffffu); dst[(size_t)8 * SEQ] = (bf16_t)(p01 >> 16);
;                 dst[(size_t)16 * SEQ] = (bf16_t)(p23 & 0xffffu); dst[(size_t)24 * SEQ] = (bf16_t)(p23 >> 16);
.Lgj_6:
	v_add_u32_e32 v182, v244, v192
	v_add_u32_e32 v183, v215, v192
	ds_read_b128 v[170:173], v182 offset:32768
	ds_read_b128 v[194:197], v183
	ds_read_b128 v[198:201], v182 offset:36864
	ds_read_b128 v[202:205], v182 offset:40960
	ds_read_b128 v[206:209], v182 offset:45056
	ds_read_b128 v[216:219], v183 offset:4096
	s_waitcnt lgkmcnt(10)
	v_mfma_f32_32x32x16_bf16 v[112:127], v[220:223], v[236:239], v[112:127]
	s_waitcnt lgkmcnt(9)
	v_mfma_f32_32x32x16_bf16 v[96:111], v[224:227], v[236:239], v[96:111]
	v_lshl_add_u64 v[248:249], v[246:247], 0, s[42:43]
	s_mov_b32 m0, s22
	v_readfirstlane_b32 s22, v250
	v_add_u32_e32 v245, 0xe000, v245
	global_load_lds_dwordx4 v[248:249], off
	s_waitcnt lgkmcnt(8)
	v_mfma_f32_32x32x16_bf16 v[80:95], v[228:231], v[236:239], v[80:95]
	s_waitcnt lgkmcnt(7)
	v_mfma_f32_32x32x16_bf16 v[64:79], v[232:235], v[236:239], v[64:79]
	v_lshl_add_u64 v[248:249], v[246:247], 0, s[40:41]
	s_mov_b32 m0, s22
	v_readfirstlane_b32 s22, v245
	global_load_lds_dwordx4 v[248:249], off
	s_waitcnt lgkmcnt(6)
	v_mfma_f32_32x32x16_bf16 v[48:63], v[220:223], v[240:243], v[48:63]
	v_mfma_f32_32x32x16_bf16 v[32:47], v[224:227], v[240:243], v[32:47]
	v_lshl_add_u64 v[246:247], v[246:247], 0, s[44:45]
	s_mov_b32 m0, s22
	s_add_i32 s9, s9, 0
	global_load_lds_dwordx4 v[246:247], off
	v_mfma_f32_32x32x16_bf16 v[16:31], v[228:231], v[240:243], v[16:31]
	v_mfma_f32_32x32x16_bf16 v[0:15], v[232:235], v[240:243], v[0:15]
	v_add_u32_e32 v184, v244, v193
	v_add_u32_e32 v185, v215, v193
	ds_read_b128 v[220:223], v184 offset:32768
	ds_read_b128 v[236:239], v185
	ds_read_b128 v[224:227], v184 offset:36864
	ds_read_b128 v[228:231], v184 offset:40960
	ds_read_b128 v[232:235], v184 offset:45056
	ds_read_b128 v[240:243], v185 offset:4096
	s_waitcnt lgkmcnt(10)
	v_mfma_f32_32x32x16_bf16 v[112:127], v[170:173], v[194:197], v[112:127]
	s_waitcnt lgkmcnt(9)
	v_mfma_f32_32x32x16_bf16 v[96:111], v[198:201], v[194:197], v[96:111]
	s_waitcnt lgkmcnt(8)
	v_mfma_f32_32x32x16_bf16 v[80:95], v[202:205], v[194:197], v[80:95]
	s_waitcnt lgkmcnt(7)
	v_mfma_f32_32x32x16_bf16 v[64:79], v[206:209], v[194:197], v[64:79]
	s_waitcnt lgkmcnt(6)
	v_mfma_f32_32x32x16_bf16 v[48:63], v[170:173], v[216:219], v[48:63]
	v_mfma_f32_32x32x16_bf16 v[32:47], v[198:201], v[216:219], v[32:47]
	v_mfma_f32_32x32x16_bf16 v[16:31], v[202:205], v[216:219], v[16:31]
	v_mfma_f32_32x32x16_bf16 v[0:15], v[206:209], v[216:219], v[0:15]
	s_waitcnt lgkmcnt(4)
	v_mfma_f32_32x32x16_bf16 v[112:127], v[220:223], v[236:239], v[112:127]
	s_waitcnt lgkmcnt(3)
	v_mfma_f32_32x32x16_bf16 v[96:111], v[224:227], v[236:239], v[96:111]
	s_waitcnt lgkmcnt(2)
	v_mfma_f32_32x32x16_bf16 v[80:95], v[228:231], v[236:239], v[80:95]
	s_waitcnt lgkmcnt(1)
	v_mfma_f32_32x32x16_bf16 v[64:79], v[232:235], v[236:239], v[64:79]
	s_waitcnt lgkmcnt(0)
	v_mfma_f32_32x32x16_bf16 v[48:63], v[220:223], v[240:243], v[48:63]
	v_mfma_f32_32x32x16_bf16 v[32:47], v[224:227], v[240:243], v[32:47]
	v_mfma_f32_32x32x16_bf16 v[16:31], v[228:231], v[240:243], v[16:31]
	v_mfma_f32_32x32x16_bf16 v[0:15], v[232:235], v[240:243], v[0:15]
	s_waitcnt vmcnt(0)
	s_and_b32 s9, s8, 15
	s_cmp_lg_u32 s9, 15
	s_cbranch_scc1 .LBB0_1107
	s_lshl_b32 s8, s8, 1
	s_and_b32 s8, s8, 0x7fffffe0
	s_add_i32 s8, s8, s33
	s_lshr_b32 s9, s8, 3
	s_and_b32 s9, s9, 12
	s_or_b32 s9, s9, s46
	s_lshl_b32 s28, s9, 8
	s_cmpk_lt_u32 s8, 0x80
	v_lshl_add_u64 v[170:171], s[28:29], 0, v[134:135]
	s_cselect_b32 s8, s11, s31
	s_cselect_b32 s9, s10, s30
	v_mov_b32_e32 v172, s9
	v_mov_b32_e32 v173, s8
	v_and_b32_e32 v175, 0x7fffffff, v171
	v_and_b32_e32 v174, 0xfffff000, v170
	v_and_b32_e32 v128, 0xfc0, v170
	v_lshl_add_u64 v[172:173], v[174:175], 1, v[172:173]
	v_lshlrev_b32_e32 v128, 1, v128
	v_lshl_add_u64 v[170:171], v[172:173], 0, v[128:129]
	v_mov_b32_e32 v169, v129
	v_lshl_add_u64 v[170:171], v[170:171], 0, v[168:169]
	v_cvt_pk_bf16_f32 v128, v112, v113
	v_lshl_add_u64 v[112:113], v[170:171], 0, v[136:137]
	s_mov_b32 s8, 0x10000
	v_cvt_pk_bf16_f32 v169, v114, v115
	v_add_co_u32_e32 v114, vcc, s8, v112
	s_mov_b32 s9, 0x20000
	s_nop 0
	v_addc_co_u32_e32 v115, vcc, 0, v113, vcc
	v_add_co_u32_e32 v172, vcc, s9, v112
	s_mov_b32 s22, 0x30000
	s_nop 0
	v_addc_co_u32_e32 v173, vcc, 0, v113, vcc
	v_add_co_u32_e32 v174, vcc, s22, v112
	global_store_short v[112:113], v128, off
	global_store_short_d16_hi v[114:115], v128, off
	v_addc_co_u32_e32 v175, vcc, 0, v113, vcc
	v_cvt_pk_bf16_f32 v128, v116, v117
	v_lshl_add_u64 v[116:117], v[170:171], 0, v[138:139]
	global_store_short v[172:173], v169, off
	global_store_short_d16_hi v[174:175], v169, off
	v_cvt_pk_bf16_f32 v169, v118, v119
	v_add_co_u32_e32 v118, vcc, s8, v116
	global_store_short v[116:117], v128, off
	s_nop 0
	v_addc_co_u32_e32 v119, vcc, 0, v117, vcc
	global_store_short_d16_hi v[118:119], v128, off
	v_add_co_u32_e32 v118, vcc, s9, v116
	v_cvt_pk_bf16_f32 v120, v120, v121
	s_nop 0
	v_addc_co_u32_e32 v119, vcc, 0, v117, vcc
	v_add_co_u32_e32 v116, vcc, s22, v116
	global_store_short v[118:119], v169, off
	s_nop 0
	v_addc_co_u32_e32 v117, vcc, 0, v117, vcc
	global_store_short_d16_hi v[116:117], v169, off
	v_lshl_add_u64 v[116:117], v[170:171], 0, v[140:141]
	v_add_co_u32_e32 v118, vcc, s8, v116
	global_store_short v[116:117], v120, off
	s_nop 0
	v_addc_co_u32_e32 v119, vcc, 0, v117, vcc
	global_store_short_d16_hi v[118:119], v120, off
	v_add_co_u32_e32 v118, vcc, s9, v116
	v_cvt_pk_bf16_f32 v121, v122, v123
	s_nop 0
	v_addc_co_u32_e32 v119, vcc, 0, v117, vcc
	v_add_co_u32_e32 v116, vcc, s22, v116
	global_store_short v[118:119], v121, off
	s_nop 0
	v_addc_co_u32_e32 v117, vcc, 0, v117, vcc
	global_store_short_d16_hi v[116:117], v121, off
; DI unsigned pack2(float a, float b) { f32x2_t v = {a, b}; return __builtin_bit_cast(unsigned, __builtin_convertvector(v, bf16x2_t)); }
;     ...
;             for (int g = 0; g < 4; ++g) {
;               const int n = nt * 256 + wn * 128 + ni * 32 + 8 * g + 4 * hh;
;               const float a0 = acc[mi][ni][4 * g], a1 = acc[mi][ni][4 * g + 1], a2 = acc[mi][ni][4 * g + 2], a3 = acc[mi][ni][4 * g + 3];
;               if (MODE == 0) {
;                 uint2 pk; pk.x = pack2(a0, a1); pk.y = pack2(a2, a3);
;                 if (outp != nullptr && nt >= 32) *(uint2*)(outp + m * 2048 + (n - 8192)) = pk;
;                 else if (n < nvalid) *(uint2*)(C + m * ldc + n) = pk;
;               } else if (MODE == 2) {
;                 const unsigned p01 = pack2(a0, a1), p23 = pack2(a2, a3);
;                 bf16_t* dst = ((nt < 8) ? C : outp) + ((size_t)(n & 2047) * 8 + (m >> 12)) * SEQ + (m & 4095);
;                 dst[0] = (bf16_t)(p01 & 0xffffu); dst[(size_t)8 * SEQ] = (bf16_t)(p01 >> 16);
;                 dst[(size_t)16 * SEQ] = (bf16_t)(p23 & 0xffffu); dst[(size_t)24 * SEQ] = (bf16_t)(p23 >> 16);
	v_lshl_add_u64 v[116:117], v[170:171], 0, v[142:143]
	v_add_co_u32_e32 v118, vcc, s8, v116
	v_cvt_pk_bf16_f32 v120, v124, v125
	s_nop 0
	v_addc_co_u32_e32 v119, vcc, 0, v117, vcc
	global_store_short_d16_hi v[118:119], v120, off
	v_add_co_u32_e32 v118, vcc, s9, v116
	global_store_short v[116:117], v120, off
	s_nop 0
	v_addc_co_u32_e32 v119, vcc, 0, v117, vcc
	v_add_co_u32_e32 v116, vcc, s22, v116
	v_cvt_pk_bf16_f32 v121, v126, v127
	s_nop 0
	v_addc_co_u32_e32 v117, vcc, 0, v117, vcc
	global_store_short v[118:119], v121, off
	global_store_short_d16_hi v[116:117], v121, off
	v_cvt_pk_bf16_f32 v116, v96, v97
	v_lshl_add_u64 v[96:97], v[170:171], 0, v[144:145]
	v_cvt_pk_bf16_f32 v117, v98, v99
	v_add_co_u32_e32 v98, vcc, s8, v96
	global_store_short v[96:97], v116, off
	s_nop 0
	v_addc_co_u32_e32 v99, vcc, 0, v97, vcc
	global_store_short_d16_hi v[98:99], v116, off
	v_add_co_u32_e32 v98, vcc, s9, v96
	v_cvt_pk_bf16_f32 v100, v100, v101
	s_nop 0
	v_addc_co_u32_e32 v99, vcc, 0, v97, vcc
	v_add_co_u32_e32 v96, vcc, s22, v96
	global_store_short v[98:99], v117, off
	s_nop 0
	v_addc_co_u32_e32 v97, vcc, 0, v97, vcc
	global_store_short_d16_hi v[96:97], v117, off
	v_lshl_add_u64 v[96:97], v[170:171], 0, v[146:147]
	v_add_co_u32_e32 v98, vcc, s8, v96
	global_store_short v[96:97], v100, off
	s_nop 0
	v_addc_co_u32_e32 v99, vcc, 0, v97, vcc
	global_store_short_d16_hi v[98:99], v100, off
	v_add_co_u32_e32 v98, vcc, s9, v96
	v_cvt_pk_bf16_f32 v101, v102, v103
	s_nop 0
	v_addc_co_u32_e32 v99, vcc, 0, v97, vcc
	v_add_co_u32_e32 v96, vcc, s22, v96
	global_store_short v[98:99], v101, off
	s_nop 0
	v_addc_co_u32_e32 v97, vcc, 0, v97, vcc
	global_store_short_d16_hi v[96:97], v101, off
	v_lshl_add_u64 v[96:97], v[170:171], 0, v[148:149]
	v_add_co_u32_e32 v98, vcc, s8, v96
	v_cvt_pk_bf16_f32 v100, v104, v105
	s_nop 0
	v_addc_co_u32_e32 v99, vcc, 0, v97, vcc
	global_store_short_d16_hi v[98:99], v100, off
	v_add_co_u32_e32 v98, vcc, s9, v96
	global_store_short v[96:97], v100, off
	s_nop 0
	v_addc_co_u32_e32 v99, vcc, 0, v97, vcc
	v_add_co_u32_e32 v96, vcc, s22, v96
	v_cvt_pk_bf16_f32 v101, v106, v107
	s_nop 0
	v_addc_co_u32_e32 v97, vcc, 0, v97, vcc
	global_store_short_d16_hi v[96:97], v101, off
	v_lshl_add_u64 v[96:97], v[170:171], 0, v[150:151]
	global_store_short v[98:99], v101, off
	v_add_co_u32_e32 v98, vcc, s8, v96
	v_cvt_pk_bf16_f32 v100, v108, v109
	s_nop 0
	v_addc_co_u32_e32 v99, vcc, 0, v97, vcc
	global_store_short_d16_hi v[98:99], v100, off
	v_add_co_u32_e32 v98, vcc, s9, v96
	global_store_short v[96:97], v100, off
	s_nop 0
	v_addc_co_u32_e32 v99, vcc, 0, v97, vcc
	v_add_co_u32_e32 v96, vcc, s22, v96
	v_cvt_pk_bf16_f32 v101, v110, v111
	s_nop 0
	v_addc_co_u32_e32 v97, vcc, 0, v97, vcc
	global_store_short v[98:99], v101, off
	global_store_short_d16_hi v[96:97], v101, off
	v_cvt_pk_bf16_f32 v96, v80, v81
	v_lshl_add_u64 v[80:81], v[170:171], 0, v[152:153]
	v_cvt_pk_bf16_f32 v97, v82, v83
	v_add_co_u32_e32 v82, vcc, s8, v80
	global_store_short v[80:81], v96, off
	s_nop 0
	v_addc_co_u32_e32 v83, vcc, 0, v81, vcc
	global_store_short_d16_hi v[82:83], v96, off
	v_add_co_u32_e32 v82, vcc, s9, v80
	v_cvt_pk_bf16_f32 v84, v84, v85
	s_nop 0
	v_addc_co_u32_e32 v83, vcc, 0, v81, vcc
	v_add_co_u32_e32 v80, vcc, s22, v80
	global_store_short v[82:83], v97, off
	s_nop 0
	v_addc_co_u32_e32 v81, vcc, 0, v81, vcc
	global_store_short_d16_hi v[80:81], v97, off
	v_lshl_add_u64 v[80:81], v[170:171], 0, v[154:155]
	v_add_co_u32_e32 v82, vcc, s8, v80
	global_store_short v[80:81], v84, off
	s_nop 0
	v_addc_co_u32_e32 v83, vcc, 0, v81, vcc
	global_store_short_d16_hi v[82:83], v84, off
	v_add_co_u32_e32 v82, vcc, s9, v80
	v_cvt_pk_bf16_f32 v85, v86, v87
	s_nop 0
	v_addc_co_u32_e32 v83, vcc, 0, v81, vcc
	v_add_co_u32_e32 v80, vcc, s22, v80
	global_store_short v[82:83], v85, off
	s_nop 0
	v_addc_co_u32_e32 v81, vcc, 0, v81, vcc
	global_store_short_d16_hi v[80:81], v85, off
	v_lshl_add_u64 v[80:81], v[170:171], 0, v[156:157]
	v_add_co_u32_e32 v82, vcc, s8, v80
	v_cvt_pk_bf16_f32 v84, v88, v89
	s_nop 0
	v_addc_co_u32_e32 v83, vcc, 0, v81, vcc
	global_store_short_d16_hi v[82:83], v84, off
	v_add_co_u32_e32 v82, vcc, s9, v80
	global_store_short v[80:81], v84, off
	s_nop 0
	v_addc_co_u32_e32 v83, vcc, 0, v81, vcc
	v_add_co_u32_e32 v80, vcc, s22, v80
	v_cvt_pk_bf16_f32 v85, v90, v91
	s_nop 0
	v_addc_co_u32_e32 v81, vcc, 0, v81, vcc
	global_store_short_d16_hi v[80:81], v85, off
	v_lshl_add_u64 v[80:81], v[170:171], 0, v[158:159]
	global_store_short v[82:83], v85, off
	v_add_co_u32_e32 v82, vcc, s8, v80
	v_cvt_pk_bf16_f32 v84, v92, v93
	s_nop 0
	v_addc_co_u32_e32 v83, vcc, 0, v81, vcc
	global_store_short_d16_hi v[82:83], v84, off
	v_add_co_u32_e32 v82, vcc, s9, v80
	global_store_short v[80:81], v84, off
	s_nop 0
	v_addc_co_u32_e32 v83, vcc, 0, v81, vcc
	v_add_co_u32_e32 v80, vcc, s22, v80
	v_cvt_pk_bf16_f32 v85, v94, v95
	s_nop 0
	v_addc_co_u32_e32 v81, vcc, 0, v81, vcc
	global_store_short v[82:83], v85, off
	global_store_short_d16_hi v[80:81], v85, off
	v_cvt_pk_bf16_f32 v80, v64, v65
	v_lshl_add_u64 v[64:65], v[170:171], 0, v[160:161]
	v_cvt_pk_bf16_f32 v81, v66, v67
	v_add_co_u32_e32 v66, vcc, s8, v64
	global_store_short v[64:65], v80, off
	s_nop 0
	v_addc_co_u32_e32 v67, vcc, 0, v65, vcc
	global_store_short_d16_hi v[66:67], v80, off
	v_add_co_u32_e32 v66, vcc, s9, v64
	v_cvt_pk_bf16_f32 v68, v68, v69
	s_nop 0
	v_addc_co_u32_e32 v67, vcc, 0, v65, vcc
	v_add_co_u32_e32 v64, vcc, s22, v64
	global_store_short v[66:67], v81, off
	s_nop 0
	v_addc_co_u32_e32 v65, vcc, 0, v65, vcc
	global_store_short_d16_hi v[64:65], v81, off
	v_lshl_add_u64 v[64:65], v[170:171], 0, v[162:163]
; DI unsigned pack2(float a, float b) { f32x2_t v = {a, b}; return __builtin_bit_cast(unsigned, __builtin_convertvector(v, bf16x2_t)); }
;     ...
;             for (int g = 0; g < 4; ++g) {
;               const int n = nt * 256 + wn * 128 + ni * 32 + 8 * g + 4 * hh;
;               const float a0 = acc[mi][ni][4 * g], a1 = acc[mi][ni][4 * g + 1], a2 = acc[mi][ni][4 * g + 2], a3 = acc[mi][ni][4 * g + 3];
;               if (MODE == 0) {
;                 uint2 pk; pk.x = pack2(a0, a1); pk.y = pack2(a2, a3);
;                 if (outp != nullptr && nt >= 32) *(uint2*)(outp + m * 2048 + (n - 8192)) = pk;
;                 else if (n < nvalid) *(uint2*)(C + m * ldc + n) = pk;
;               } else if (MODE == 2) {
;                 const unsigned p01 = pack2(a0, a1), p23 = pack2(a2, a3);
;                 bf16_t* dst = ((nt < 8) ? C : outp) + ((size_t)(n & 2047) * 8 + (m >> 12)) * SEQ + (m & 4095);
;                 dst[0] = (bf16_t)(p01 & 0xffffu); dst[(size_t)8 * SEQ] = (bf16_t)(p01 >> 16);
;                 dst[(size_t)16 * SEQ] = (bf16_t)(p23 & 0xffffu); dst[(size_t)24 * SEQ] = (bf16_t)(p23 >> 16);
	v_add_co_u32_e32 v66, vcc, s8, v64
	global_store_short v[64:65], v68, off
	s_nop 0
	v_addc_co_u32_e32 v67, vcc, 0, v65, vcc
	global_store_short_d16_hi v[66:67], v68, off
	v_add_co_u32_e32 v66, vcc, s9, v64
	v_cvt_pk_bf16_f32 v69, v70, v71
	s_nop 0
	v_addc_co_u32_e32 v67, vcc, 0, v65, vcc
	v_add_co_u32_e32 v64, vcc, s22, v64
	global_store_short v[66:67], v69, off
	s_nop 0
	v_addc_co_u32_e32 v65, vcc, 0, v65, vcc
	global_store_short_d16_hi v[64:65], v69, off
	v_lshl_add_u64 v[64:65], v[170:171], 0, v[164:165]
	v_add_co_u32_e32 v66, vcc, s8, v64
	v_cvt_pk_bf16_f32 v68, v72, v73
	s_nop 0
	v_addc_co_u32_e32 v67, vcc, 0, v65, vcc
	global_store_short_d16_hi v[66:67], v68, off
	v_add_co_u32_e32 v66, vcc, s9, v64
	global_store_short v[64:65], v68, off
	s_nop 0
	v_addc_co_u32_e32 v67, vcc, 0, v65, vcc
	v_add_co_u32_e32 v64, vcc, s22, v64
	v_cvt_pk_bf16_f32 v69, v74, v75
	s_nop 0
	v_addc_co_u32_e32 v65, vcc, 0, v65, vcc
	global_store_short_d16_hi v[64:65], v69, off
	v_lshl_add_u64 v[64:65], v[170:171], 0, v[166:167]
	global_store_short v[66:67], v69, off
	v_add_co_u32_e32 v66, vcc, s8, v64
	v_cvt_pk_bf16_f32 v68, v76, v77
	s_nop 0
	v_addc_co_u32_e32 v67, vcc, 0, v65, vcc
	global_store_short_d16_hi v[66:67], v68, off
	v_add_co_u32_e32 v66, vcc, s9, v64
	global_store_short v[64:65], v68, off
	s_nop 0
	v_addc_co_u32_e32 v67, vcc, 0, v65, vcc
	v_add_co_u32_e32 v64, vcc, s22, v64
	v_cvt_pk_bf16_f32 v69, v78, v79
	s_nop 0
	v_addc_co_u32_e32 v65, vcc, 0, v65, vcc
	global_store_short_d16_hi v[64:65], v69, off
	v_lshl_add_u64 v[64:65], v[170:171], 0, 64
	global_store_short v[66:67], v69, off
	v_cvt_pk_bf16_f32 v48, v48, v49
	v_cvt_pk_bf16_f32 v49, v50, v51
	global_store_short v[112:113], v48, off offset:64
	global_store_short_d16_hi v[114:115], v48, off offset:64
	global_store_short v[172:173], v49, off offset:64
	global_store_short_d16_hi v[174:175], v49, off offset:64
	v_lshl_add_u64 v[48:49], v[64:65], 0, v[138:139]
	v_add_co_u32_e32 v50, vcc, s8, v48
	v_cvt_pk_bf16_f32 v52, v52, v53
	s_nop 0
	v_addc_co_u32_e32 v51, vcc, 0, v49, vcc
	global_store_short_d16_hi v[50:51], v52, off
	v_add_co_u32_e32 v50, vcc, s9, v48
	global_store_short v[48:49], v52, off
	s_nop 0
	v_addc_co_u32_e32 v51, vcc, 0, v49, vcc
	v_add_co_u32_e32 v48, vcc, s22, v48
	v_cvt_pk_bf16_f32 v53, v54, v55
	s_nop 0
	v_addc_co_u32_e32 v49, vcc, 0, v49, vcc
	global_store_short_d16_hi v[48:49], v53, off
	v_lshl_add_u64 v[48:49], v[64:65], 0, v[140:141]
	global_store_short v[50:51], v53, off
	v_add_co_u32_e32 v50, vcc, s8, v48
	v_cvt_pk_bf16_f32 v52, v56, v57
	s_nop 0
	v_addc_co_u32_e32 v51, vcc, 0, v49, vcc
	global_store_short_d16_hi v[50:51], v52, off
	v_add_co_u32_e32 v50, vcc, s9, v48
	global_store_short v[48:49], v52, off
	s_nop 0
	v_addc_co_u32_e32 v51, vcc, 0, v49, vcc
	v_add_co_u32_e32 v48, vcc, s22, v48
	v_cvt_pk_bf16_f32 v53, v58, v59
	s_nop 0
	v_addc_co_u32_e32 v49, vcc, 0, v49, vcc
	global_store_short_d16_hi v[48:49], v53, off
	v_lshl_add_u64 v[48:49], v[64:65], 0, v[142:143]
	global_store_short v[50:51], v53, off
	v_add_co_u32_e32 v50, vcc, s8, v48
	v_cvt_pk_bf16_f32 v52, v60, v61
	s_nop 0
	v_addc_co_u32_e32 v51, vcc, 0, v49, vcc
	global_store_short_d16_hi v[50:51], v52, off
	v_add_co_u32_e32 v50, vcc, s9, v48
	global_store_short v[48:49], v52, off
	s_nop 0
	v_addc_co_u32_e32 v51, vcc, 0, v49, vcc
	v_add_co_u32_e32 v48, vcc, s22, v48
	v_cvt_pk_bf16_f32 v53, v62, v63
	s_nop 0
	v_addc_co_u32_e32 v49, vcc, 0, v49, vcc
	global_store_short v[50:51], v53, off
	global_store_short_d16_hi v[48:49], v53, off
	v_cvt_pk_bf16_f32 v48, v32, v33
	v_lshl_add_u64 v[32:33], v[64:65], 0, v[144:145]
	v_cvt_pk_bf16_f32 v49, v34, v35
	v_add_co_u32_e32 v34, vcc, s8, v32
	global_store_short v[32:33], v48, off
	s_nop 0
	v_addc_co_u32_e32 v35, vcc, 0, v33, vcc
	global_store_short_d16_hi v[34:35], v48, off
	v_add_co_u32_e32 v34, vcc, s9, v32
	v_cvt_pk_bf16_f32 v36, v36, v37
	s_nop 0
	v_addc_co_u32_e32 v35, vcc, 0, v33, vcc
	v_add_co_u32_e32 v32, vcc, s22, v32
	global_store_short v[34:35], v49, off
	s_nop 0
	v_addc_co_u32_e32 v33, vcc, 0, v33, vcc
	global_store_short_d16_hi v[32:33], v49, off
	v_lshl_add_u64 v[32:33], v[64:65], 0, v[146:147]
	v_add_co_u32_e32 v34, vcc, s8, v32
	global_store_short v[32:33], v36, off
	s_nop 0
	v_addc_co_u32_e32 v35, vcc, 0, v33, vcc
	global_store_short_d16_hi v[34:35], v36, off
	v_add_co_u32_e32 v34, vcc, s9, v32
	v_cvt_pk_bf16_f32 v37, v38, v39
	s_nop 0
	v_addc_co_u32_e32 v35, vcc, 0, v33, vcc
	v_add_co_u32_e32 v32, vcc, s22, v32
	global_store_short v[34:35], v37, off
	s_nop 0
	v_addc_co_u32_e32 v33, vcc, 0, v33, vcc
	global_store_short_d16_hi v[32:33], v37, off
	v_lshl_add_u64 v[32:33], v[64:65], 0, v[148:149]
	v_add_co_u32_e32 v34, vcc, s8, v32
	v_cvt_pk_bf16_f32 v36, v40, v41
	s_nop 0
	v_addc_co_u32_e32 v35, vcc, 0, v33, vcc
	global_store_short_d16_hi v[34:35], v36, off
	v_add_co_u32_e32 v34, vcc, s9, v32
	global_store_short v[32:33], v36, off
	s_nop 0
	v_addc_co_u32_e32 v35, vcc, 0, v33, vcc
	v_add_co_u32_e32 v32, vcc, s22, v32
; DI unsigned pack2(float a, float b) { f32x2_t v = {a, b}; return __builtin_bit_cast(unsigned, __builtin_convertvector(v, bf16x2_t)); }
;     ...
;             for (int g = 0; g < 4; ++g) {
;               const int n = nt * 256 + wn * 128 + ni * 32 + 8 * g + 4 * hh;
;               const float a0 = acc[mi][ni][4 * g], a1 = acc[mi][ni][4 * g + 1], a2 = acc[mi][ni][4 * g + 2], a3 = acc[mi][ni][4 * g + 3];
;               if (MODE == 0) {
;                 uint2 pk; pk.x = pack2(a0, a1); pk.y = pack2(a2, a3);
;                 if (outp != nullptr && nt >= 32) *(uint2*)(outp + m * 2048 + (n - 8192)) = pk;
;                 else if (n < nvalid) *(uint2*)(C + m * ldc + n) = pk;
;               } else if (MODE == 2) {
;                 const unsigned p01 = pack2(a0, a1), p23 = pack2(a2, a3);
;                 bf16_t* dst = ((nt < 8) ? C : outp) + ((size_t)(n & 2047) * 8 + (m >> 12)) * SEQ + (m & 4095);
;                 dst[0] = (bf16_t)(p01 & 0xffffu); dst[(size_t)8 * SEQ] = (bf16_t)(p01 >> 16);
;                 dst[(size_t)16 * SEQ] = (bf16_t)(p23 & 0xffffu); dst[(size_t)24 * SEQ] = (bf16_t)(p23 >> 16);
	v_cvt_pk_bf16_f32 v37, v42, v43
	s_nop 0
	v_addc_co_u32_e32 v33, vcc, 0, v33, vcc
	global_store_short_d16_hi v[32:33], v37, off
	v_lshl_add_u64 v[32:33], v[64:65], 0, v[150:151]
	global_store_short v[34:35], v37, off
	v_add_co_u32_e32 v34, vcc, s8, v32
	v_cvt_pk_bf16_f32 v36, v44, v45
	s_nop 0
	v_addc_co_u32_e32 v35, vcc, 0, v33, vcc
	global_store_short_d16_hi v[34:35], v36, off
	v_add_co_u32_e32 v34, vcc, s9, v32
	global_store_short v[32:33], v36, off
	s_nop 0
	v_addc_co_u32_e32 v35, vcc, 0, v33, vcc
	v_add_co_u32_e32 v32, vcc, s22, v32
	v_cvt_pk_bf16_f32 v37, v46, v47
	s_nop 0
	v_addc_co_u32_e32 v33, vcc, 0, v33, vcc
	global_store_short v[34:35], v37, off
	global_store_short_d16_hi v[32:33], v37, off
	v_cvt_pk_bf16_f32 v32, v16, v17
	v_lshl_add_u64 v[16:17], v[64:65], 0, v[152:153]
	v_cvt_pk_bf16_f32 v33, v18, v19
	v_add_co_u32_e32 v18, vcc, s8, v16
	global_store_short v[16:17], v32, off
	s_nop 0
	v_addc_co_u32_e32 v19, vcc, 0, v17, vcc
	global_store_short_d16_hi v[18:19], v32, off
	v_add_co_u32_e32 v18, vcc, s9, v16
	v_cvt_pk_bf16_f32 v20, v20, v21
	s_nop 0
	v_addc_co_u32_e32 v19, vcc, 0, v17, vcc
	v_add_co_u32_e32 v16, vcc, s22, v16
	global_store_short v[18:19], v33, off
	s_nop 0
	v_addc_co_u32_e32 v17, vcc, 0, v17, vcc
	global_store_short_d16_hi v[16:17], v33, off
	v_lshl_add_u64 v[16:17], v[64:65], 0, v[154:155]
	v_add_co_u32_e32 v18, vcc, s8, v16
	global_store_short v[16:17], v20, off
	s_nop 0
	v_addc_co_u32_e32 v19, vcc, 0, v17, vcc
	global_store_short_d16_hi v[18:19], v20, off
	v_add_co_u32_e32 v18, vcc, s9, v16
	v_cvt_pk_bf16_f32 v21, v22, v23
	s_nop 0
	v_addc_co_u32_e32 v19, vcc, 0, v17, vcc
	v_add_co_u32_e32 v16, vcc, s22, v16
	global_store_short v[18:19], v21, off
	s_nop 0
	v_addc_co_u32_e32 v17, vcc, 0, v17, vcc
	global_store_short_d16_hi v[16:17], v21, off
	v_lshl_add_u64 v[16:17], v[64:65], 0, v[156:157]
	v_add_co_u32_e32 v18, vcc, s8, v16
	v_cvt_pk_bf16_f32 v20, v24, v25
	s_nop 0
	v_addc_co_u32_e32 v19, vcc, 0, v17, vcc
	global_store_short_d16_hi v[18:19], v20, off
	v_add_co_u32_e32 v18, vcc, s9, v16
	global_store_short v[16:17], v20, off
	s_nop 0
	v_addc_co_u32_e32 v19, vcc, 0, v17, vcc
	v_add_co_u32_e32 v16, vcc, s22, v16
	v_cvt_pk_bf16_f32 v21, v26, v27
	s_nop 0
	v_addc_co_u32_e32 v17, vcc, 0, v17, vcc
	global_store_short_d16_hi v[16:17], v21, off
	v_lshl_add_u64 v[16:17], v[64:65], 0, v[158:159]
	global_store_short v[18:19], v21, off
	v_add_co_u32_e32 v18, vcc, s8, v16
	v_cvt_pk_bf16_f32 v20, v28, v29
	s_nop 0
	v_addc_co_u32_e32 v19, vcc, 0, v17, vcc
	global_store_short_d16_hi v[18:19], v20, off
	v_add_co_u32_e32 v18, vcc, s9, v16
	global_store_short v[16:17], v20, off
	s_nop 0
	v_addc_co_u32_e32 v19, vcc, 0, v17, vcc
	v_add_co_u32_e32 v16, vcc, s22, v16
	v_cvt_pk_bf16_f32 v21, v30, v31
	s_nop 0
	v_addc_co_u32_e32 v17, vcc, 0, v17, vcc
	global_store_short v[18:19], v21, off
	global_store_short_d16_hi v[16:17], v21, off
	v_cvt_pk_bf16_f32 v16, v0, v1
	v_lshl_add_u64 v[0:1], v[64:65], 0, v[160:161]
	v_cvt_pk_bf16_f32 v17, v2, v3
	v_add_co_u32_e32 v2, vcc, s8, v0
	global_store_short v[0:1], v16, off
	s_nop 0
	v_addc_co_u32_e32 v3, vcc, 0, v1, vcc
	global_store_short_d16_hi v[2:3], v16, off
	v_add_co_u32_e32 v2, vcc, s9, v0
	v_cvt_pk_bf16_f32 v4, v4, v5
	s_nop 0
	v_addc_co_u32_e32 v3, vcc, 0, v1, vcc
	v_add_co_u32_e32 v0, vcc, s22, v0
	global_store_short v[2:3], v17, off
	s_nop 0
	v_addc_co_u32_e32 v1, vcc, 0, v1, vcc
	global_store_short_d16_hi v[0:1], v17, off
	v_lshl_add_u64 v[0:1], v[64:65], 0, v[162:163]
	v_add_co_u32_e32 v2, vcc, s8, v0
	global_store_short v[0:1], v4, off
	s_nop 0
	v_addc_co_u32_e32 v3, vcc, 0, v1, vcc
	global_store_short_d16_hi v[2:3], v4, off
	v_add_co_u32_e32 v2, vcc, s9, v0
	v_cvt_pk_bf16_f32 v5, v6, v7
	s_nop 0
	v_addc_co_u32_e32 v3, vcc, 0, v1, vcc
	v_add_co_u32_e32 v0, vcc, s22, v0
	global_store_short v[2:3], v5, off
	s_nop 0
	v_addc_co_u32_e32 v1, vcc, 0, v1, vcc
	global_store_short_d16_hi v[0:1], v5, off
	v_lshl_add_u64 v[0:1], v[64:65], 0, v[164:165]
	v_add_co_u32_e32 v2, vcc, s8, v0
	v_cvt_pk_bf16_f32 v4, v8, v9
	s_nop 0
	v_addc_co_u32_e32 v3, vcc, 0, v1, vcc
	global_store_short_d16_hi v[2:3], v4, off
	v_add_co_u32_e32 v2, vcc, s9, v0
	global_store_short v[0:1], v4, off
	s_nop 0
	v_addc_co_u32_e32 v3, vcc, 0, v1, vcc
	v_add_co_u32_e32 v0, vcc, 0x30000, v0
	v_cvt_pk_bf16_f32 v5, v10, v11
	s_nop 0
	v_addc_co_u32_e32 v1, vcc, 0, v1, vcc
	global_store_short_d16_hi v[0:1], v5, off
	v_lshl_add_u64 v[0:1], v[64:65], 0, v[166:167]
	global_store_short v[2:3], v5, off
	v_add_co_u32_e32 v2, vcc, 0x10000, v0
	v_cvt_pk_bf16_f32 v4, v12, v13
	s_nop 0
	v_addc_co_u32_e32 v3, vcc, 0, v1, vcc
	global_store_short_d16_hi v[2:3], v4, off
	v_add_co_u32_e32 v2, vcc, 0x20000, v0
	global_store_short v[0:1], v4, off
	s_nop 0
	v_addc_co_u32_e32 v3, vcc, 0, v1, vcc
	v_add_co_u32_e32 v0, vcc, 0x30000, v0
	v_cvt_pk_bf16_f32 v5, v14, v15
	s_nop 0
	v_addc_co_u32_e32 v1, vcc, 0, v1, vcc
	global_store_short_d16_hi v[0:1], v5, off
	global_store_short v[2:3], v5, off
	s_branch .LBB0_1107

; __device__ __forceinline__ unsigned xb_ld(unsigned* p)              { return __hip_atomic_load(p, __ATOMIC_RELAXED, __HIP_MEMORY_SCOPE_AGENT); }
; __device__ __forceinline__ unsigned xb_add(unsigned* p, unsigned v) { return __hip_atomic_fetch_add(p, v, __ATOMIC_RELAXED, __HIP_MEMORY_SCOPE_AGENT); }
; #define XB_SPIN(cond, bar) do { unsigned _sp = 0; while (cond) { __builtin_amdgcn_s_sleep(1); \
;     if ((++_sp & 255u) == 0u) { if (xb_ld(&(bar)[XB_TMO])) break; if (_sp > XB_SPIN_CAP) { atomicAdd(&(bar)[XB_TMO], 1u); break; } } } } while (0)
; __device__ __forceinline__ bool xb_is_t0(int wvs) { int l; asm volatile("v_mbcnt_lo_u32_b32 %0, -1, 0\n\tv_mbcnt_hi_u32_b32 %0, -1, %0" : "=v"(l)); return wvs == 0 && l == 0; }
; __device__ __forceinline__ void xcd_barrier(const XcdBarrier& b) {
;     asm volatile("s_waitcnt vmcnt(0)" ::: "memory");
;     __syncthreads();
;     if (xb_is_t0(b.wvs)) {
;         unsigned* bar = b.bar;
;         __builtin_amdgcn_s_waitcnt(0);
;         unsigned nloc = b.st[0], nx = b.st[1];
;         if (nloc == 0u) { xcd_barrier_complete(bar, b.x, nloc, nx); b.st[0] = nloc; b.st[1] = nx; }
;         const unsigned old = xb_add(&bar[XB_XSUB(b.x)], 1u);
;         const unsigned gen = old / nloc;
;         if (old + 1u == (gen + 1u) * nloc) {
;             __builtin_amdgcn_fence(__ATOMIC_RELEASE, "agent");
;             asm volatile("s_waitcnt vmcnt(0)" ::: "memory");
;             const unsigned og = xb_add(&bar[XB_TOP], 1u);
;             const unsigned tg = og / nx;
;             if (og + 1u == (tg + 1u) * nx) xb_add(&bar[XB_TOPGEN], 1u);
;             else XB_SPIN(xb_ld(&bar[XB_TOPGEN]) == tg, bar);
;             __builtin_amdgcn_fence(__ATOMIC_ACQUIRE, "agent");
;             xb_add(&bar[XB_XGEN(b.x)], 1u);
;             asm volatile("s_waitcnt vmcnt(0)" ::: "memory");
;         } else {
;             XB_SPIN(xb_ld(&bar[XB_XGEN(b.x)]) == gen, bar);
;             __builtin_amdgcn_fence(__ATOMIC_ACQUIRE, "agent");
;             asm volatile("s_waitcnt vmcnt(0)" ::: "memory");
;         }
;     }
;     __syncthreads();
; }
.LBB0_1227:
	s_waitcnt vmcnt(0)
	v_readlane_b32 s6, v251, 3
	s_barrier
	v_mbcnt_lo_u32_b32 v0, -1, 0
	v_mbcnt_hi_u32_b32 v0, -1, v0
	v_readlane_b32 s7, v251, 4
	v_cmp_eq_u32_e32 vcc, 0, v0
	s_and_b64 s[6:7], s[6:7], vcc
	s_and_saveexec_b64 s[40:41], s[6:7]
	v_readlane_b32 s58, v255, 12
	v_readlane_b32 s59, v255, 13
	s_branch .LBB0_1279

; DI f32x16 zero16() { f32x16 z; for (int i = 0; i < 16; ++i) z[i] = 0.f; return z; }
;     ...
;   f32x16 acc[2][4];
; #pragma unroll
;   for (int i = 0; i < 2; ++i)
; #pragma unroll
;     for (int j = 0; j < 4; ++j) acc[i][j] = zero16();
.LBB0_1291:
	v_readlane_b32 s46, v252, 55
	v_readlane_b32 s47, v252, 60

; #define MFMA(a, b, c) __builtin_amdgcn_mfma_f32_32x32x16_bf16((a), (b), (c), 0, 0, 0)
;     ...
;   for (int s = 0; s < S; ++s) {
;     G_DMA(s + 1, cur ^ BUFB);
;     {
;       const char* Ab = smem + cur + fA;
;       const char* Bb = smem + cur + fB;
;       __builtin_amdgcn_sched_barrier(0);
; #pragma unroll
;       for (int kk = 0; kk < 4; ++kk) {
;         const int ko = (((kk * 2 + hh) ^ fsw) << 4);
;         bf16x8 af[2], wf[4];
;         af[0] = *(const bf16x8*)(Ab + ko); af[1] = *(const bf16x8*)(Ab + 4096 + ko);
; #pragma unroll
;         for (int ni = 0; ni < 4; ++ni) wf[ni] = *(const bf16x8*)(Bb + ni * 4096 + ko);
; #pragma unroll
;         for (int mi = 0; mi < 2; ++mi)
; #pragma unroll
;           for (int ni = 0; ni < 4; ++ni) acc[mi][ni] = MFMA(wf[ni], af[mi], acc[mi][ni]);
;         if (kk == 1) __builtin_amdgcn_sched_barrier(0);
;       }
;       __builtin_amdgcn_sched_barrier(0);
;     }
.LBB0_1293:
	v_add3_u32 v187, s23, v131, v138
	v_add3_u32 v208, s23, v139, v138
	v_add_u32_e32 v182, v208, v142
	v_add_u32_e32 v183, v187, v142
	ds_read_b128 v[192:195], v182 offset:32768
	ds_read_b128 v[216:219], v183
	ds_read_b128 v[196:199], v182 offset:36864
	ds_read_b128 v[200:203], v182 offset:40960
	ds_read_b128 v[204:207], v182 offset:45056
	ds_read_b128 v[220:223], v183 offset:4096
	v_add_u32_e32 v184, v208, v143
	v_add_u32_e32 v185, v187, v143
	ds_read_b128 v[224:227], v184 offset:32768
	ds_read_b128 v[240:243], v185
	ds_read_b128 v[228:231], v184 offset:36864
	ds_read_b128 v[232:235], v184 offset:40960
	ds_read_b128 v[236:239], v184 offset:45056
	ds_read_b128 v[244:247], v185 offset:4096
	s_add_i32 s44, s8, 1
	s_mov_b32 s9, s23
	s_cmp_lt_u32 s44, s46
	v_readlane_b32 s23, v252, 57
	s_cselect_b32 s23, s44, s23
	s_lshl_b32 s24, s23, 1
	s_andn2_b32 s24, s24, 31
	s_add_i32 s24, s24, s33
	s_lshr_b32 s24, s24, 3
	s_and_b32 s25, s24, 4
	s_or_b32 s25, s25, s47
	s_and_b32 s24, s24, 0xfffff8
	s_or_b32 s28, s24, s74
	s_lshl_b32 s24, s25, 19
	s_add_u32 s24, s7, s24
	s_addc_u32 s25, s22, 0
	s_lshl_b32 s23, s23, 7
	s_and_b32 s45, s23, 0x780
	s_add_u32 s24, s24, s45
	s_addc_u32 s25, s25, 0
	s_lshl_b32 s40, s28, 8
	s_ashr_i32 s41, s40, 31
	s_lshl_b64 s[40:41], s[40:41], 11
	s_add_u32 s28, s72, s40
	s_addc_u32 s40, s73, s41
	s_xor_b32 s23, s9, 0x10000
	v_add_u32_e32 v128, s23, v140
	v_lshl_add_u64 v[136:137], s[24:25], 0, v[132:133]
	v_readfirstlane_b32 s24, v128
	v_add_u32_e32 v148, 0x2000, v128
	s_mov_b32 m0, s24
	s_mov_b64 s[48:49], 0x20000
	v_readfirstlane_b32 s24, v148
	v_add_u32_e32 v148, 0x4000, v128
	global_load_lds_dwordx4 v[136:137], off
	s_add_i32 s9, s9, 0
	s_and_b32 s9, s8, 15
	s_cmp_eq_u32 s9, 0
	s_cbranch_scc1 .Lgz_9
	s_waitcnt lgkmcnt(10)
	v_mfma_f32_32x32x16_bf16 v[112:127], v[192:195], v[216:219], v[112:127]
	s_waitcnt lgkmcnt(9)
	v_mfma_f32_32x32x16_bf16 v[96:111], v[196:199], v[216:219], v[96:111]
	v_lshl_add_u64 v[146:147], v[136:137], 0, s[48:49]
	s_mov_b32 m0, s24
	s_mov_b64 s[50:51], 0x40000
	v_readfirstlane_b32 s24, v148
	global_load_lds_dwordx4 v[146:147], off
	s_waitcnt lgkmcnt(8)
	v_mfma_f32_32x32x16_bf16 v[80:95], v[200:203], v[216:219], v[80:95]
	s_waitcnt lgkmcnt(7)
	v_mfma_f32_32x32x16_bf16 v[64:79], v[204:207], v[216:219], v[64:79]
	v_lshl_add_u64 v[146:147], v[136:137], 0, s[50:51]
	s_mov_b32 m0, s24
	s_mov_b64 s[52:53], 0x60000
	global_load_lds_dwordx4 v[146:147], off
	s_waitcnt lgkmcnt(6)
	v_mfma_f32_32x32x16_bf16 v[48:63], v[192:195], v[220:223], v[48:63]
	v_mfma_f32_32x32x16_bf16 v[32:47], v[196:199], v[220:223], v[32:47]
	v_add_u32_e32 v146, 0x6000, v128
	v_lshl_add_u64 v[136:137], v[136:137], 0, s[52:53]
	v_readfirstlane_b32 s24, v146
	s_mov_b32 m0, s24
	s_add_u32 s24, s28, s45
	s_addc_u32 s25, s40, 0
	v_add_u32_e32 v146, 0x8000, v128
	global_load_lds_dwordx4 v[136:137], off
	v_mfma_f32_32x32x16_bf16 v[16:31], v[200:203], v[220:223], v[16:31]
	v_mfma_f32_32x32x16_bf16 v[0:15], v[204:207], v[220:223], v[0:15]
	v_lshl_add_u64 v[136:137], s[24:25], 0, v[132:133]
	v_readfirstlane_b32 s24, v146
	v_add_u32_e32 v148, 0xa000, v128
	s_mov_b32 m0, s24
	v_readfirstlane_b32 s24, v148
	v_add_u32_e32 v148, 0xc000, v128
	global_load_lds_dwordx4 v[136:137], off
	s_branch .Lgj_9
.Lgz_9:
	s_waitcnt lgkmcnt(10)
	v_mfma_f32_32x32x16_bf16 v[112:127], v[192:195], v[216:219], 0
	s_waitcnt lgkmcnt(9)
	v_mfma_f32_32x32x16_bf16 v[96:111], v[196:199], v[216:219], 0
	v_lshl_add_u64 v[146:147], v[136:137], 0, s[48:49]
	s_mov_b32 m0, s24
	s_mov_b64 s[50:51], 0x40000
	v_readfirstlane_b32 s24, v148
	global_load_lds_dwordx4 v[146:147], off
	s_waitcnt lgkmcnt(8)
	v_mfma_f32_32x32x16_bf16 v[80:95], v[200:203], v[216:219], 0
	s_waitcnt lgkmcnt(7)
	v_mfma_f32_32x32x16_bf16 v[64:79], v[204:207], v[216:219], 0
	v_lshl_add_u64 v[146:147], v[136:137], 0, s[50:51]
	s_mov_b32 m0, s24
	s_mov_b64 s[52:53], 0x60000
	global_load_lds_dwordx4 v[146:147], off
	s_waitcnt lgkmcnt(6)
	v_mfma_f32_32x32x16_bf16 v[48:63], v[192:195], v[220:223], 0
	v_mfma_f32_32x32x16_bf16 v[32:47], v[196:199], v[220:223], 0
	v_add_u32_e32 v146, 0x6000, v128
	v_lshl_add_u64 v[136:137], v[136:137], 0, s[52:53]
	v_readfirstlane_b32 s24, v146
	s_mov_b32 m0, s24
	s_add_u32 s24, s28, s45
	s_addc_u32 s25, s40, 0
	v_add_u32_e32 v146, 0x8000, v128
	global_load_lds_dwordx4 v[136:137], off
	v_mfma_f32_32x32x16_bf16 v[16:31], v[200:203], v[220:223], 0
	v_mfma_f32_32x32x16_bf16 v[0:15], v[204:207], v[220:223], 0
	v_lshl_add_u64 v[136:137], s[24:25], 0, v[132:133]
	v_readfirstlane_b32 s24, v146
	v_add_u32_e32 v148, 0xa000, v128
	s_mov_b32 m0, s24
	v_readfirstlane_b32 s24, v148
	v_add_u32_e32 v148, 0xc000, v128
	global_load_lds_dwordx4 v[136:137], off
; #define MFMA(a, b, c) __builtin_amdgcn_mfma_f32_32x32x16_bf16((a), (b), (c), 0, 0, 0)
; DI unsigned pack2(float a, float b) { f32x2_t v = {a, b}; return __builtin_bit_cast(unsigned, __builtin_convertvector(v, bf16x2_t)); }
;     ...
;       for (int kk = 0; kk < 4; ++kk) {
;         const int ko = (((kk * 2 + hh) ^ fsw) << 4);
;         bf16x8 af[2], wf[4];
;         af[0] = *(const bf16x8*)(Ab + ko); af[1] = *(const bf16x8*)(Ab + 4096 + ko);
; #pragma unroll
;         for (int ni = 0; ni < 4; ++ni) wf[ni] = *(const bf16x8*)(Bb + ni * 4096 + ko);
; #pragma unroll
;         for (int mi = 0; mi < 2; ++mi)
; #pragma unroll
;           for (int ni = 0; ni < 4; ++ni) acc[mi][ni] = MFMA(wf[ni], af[mi], acc[mi][ni]);
;         if (kk == 1) __builtin_amdgcn_sched_barrier(0);
;       }
;       __builtin_amdgcn_sched_barrier(0);
;     }
;     asm volatile("s_waitcnt vmcnt(0)" ::: "memory");
;     if ((s & (nk - 1)) == nk - 1) {
;       const int q = slot + (s >> lnk) * nslots;
;       int mt, nt; G_TILEMAP(q, mt, nt);
;       if (dostore) {
; #pragma unroll
;         for (int mi = 0; mi < 2; ++mi) {
;           const size_t m = (size_t)mt * 256 + wm * 64 + mi * 32 + r;
; #pragma unroll
;           for (int ni = 0; ni < 4; ++ni) {
;             __builtin_amdgcn_sched_barrier(0);
;             if (MODE == 0) {
; #pragma unroll
;               for (int gp = 0; gp < 2; ++gp) {
;                 const int g0 = 2 * gp;
;                 uint2 pa, pb;
;                 pa.x = pack2(acc[mi][ni][4 * g0], acc[mi][ni][4 * g0 + 1]); pa.y = pack2(acc[mi][ni][4 * g0 + 2], acc[mi][ni][4 * g0 + 3]);
;                 pb.x = pack2(acc[mi][ni][4 * g0 + 4], acc[mi][ni][4 * g0 + 5]); pb.y = pack2(acc[mi][ni][4 * g0 + 6], acc[mi][ni][4 * g0 + 7]);
;                 { auto rx = __builtin_amdgcn_permlane32_swap(pa.x, pb.x, false, false); pa.x = rx[0]; pb.x = rx[1]; }
;                 { auto ry = __builtin_amdgcn_permlane32_swap(pa.y, pb.y, false, false); pa.y = ry[0]; pb.y = ry[1]; }
;                 const int col = nt * 256 + wn * 128 + ni * 32 + 8 * g0 + 8 * hh;
;                 const uint4 v4 = make_uint4(pa.x, pa.y, pb.x, pb.y);
;                 if (outp != nullptr && nt >= 32) *(uint4*)(outp + m * 2048 + (col - 8192)) = v4;
;                 else if (col < nvalid) *(uint4*)(C + m * ldc + col) = v4;
.Lgj_9:
	v_add_u32_e32 v182, v208, v144
	v_add_u32_e32 v183, v187, v144
	ds_read_b128 v[192:195], v182 offset:32768
	ds_read_b128 v[216:219], v183
	ds_read_b128 v[196:199], v182 offset:36864
	ds_read_b128 v[200:203], v182 offset:40960
	ds_read_b128 v[204:207], v182 offset:45056
	ds_read_b128 v[220:223], v183 offset:4096
	s_waitcnt lgkmcnt(10)
	v_mfma_f32_32x32x16_bf16 v[112:127], v[224:227], v[240:243], v[112:127]
	s_waitcnt lgkmcnt(9)
	v_mfma_f32_32x32x16_bf16 v[96:111], v[228:231], v[240:243], v[96:111]
	v_lshl_add_u64 v[146:147], v[136:137], 0, s[48:49]
	s_mov_b32 m0, s24
	v_readfirstlane_b32 s24, v148
	v_add_u32_e32 v128, 0xe000, v128
	global_load_lds_dwordx4 v[146:147], off
	s_waitcnt lgkmcnt(8)
	v_mfma_f32_32x32x16_bf16 v[80:95], v[232:235], v[240:243], v[80:95]
	s_waitcnt lgkmcnt(7)
	v_mfma_f32_32x32x16_bf16 v[64:79], v[236:239], v[240:243], v[64:79]
	v_lshl_add_u64 v[146:147], v[136:137], 0, s[50:51]
	s_mov_b32 m0, s24
	v_readfirstlane_b32 s24, v128
	global_load_lds_dwordx4 v[146:147], off
	s_waitcnt lgkmcnt(6)
	v_mfma_f32_32x32x16_bf16 v[48:63], v[224:227], v[244:247], v[48:63]
	v_mfma_f32_32x32x16_bf16 v[32:47], v[228:231], v[244:247], v[32:47]
	v_lshl_add_u64 v[136:137], v[136:137], 0, s[52:53]
	s_mov_b32 m0, s24
	s_mov_b64 s[48:49], 0x40000
	global_load_lds_dwordx4 v[136:137], off
	v_mfma_f32_32x32x16_bf16 v[16:31], v[232:235], v[244:247], v[16:31]
	v_mfma_f32_32x32x16_bf16 v[0:15], v[236:239], v[244:247], v[0:15]
	v_add_u32_e32 v184, v208, v145
	v_add_u32_e32 v185, v187, v145
	ds_read_b128 v[224:227], v184 offset:32768
	ds_read_b128 v[240:243], v185
	ds_read_b128 v[228:231], v184 offset:36864
	ds_read_b128 v[232:235], v184 offset:40960
	ds_read_b128 v[236:239], v184 offset:45056
	ds_read_b128 v[244:247], v185 offset:4096
	s_waitcnt lgkmcnt(10)
	v_mfma_f32_32x32x16_bf16 v[112:127], v[192:195], v[216:219], v[112:127]
	s_waitcnt lgkmcnt(9)
	v_mfma_f32_32x32x16_bf16 v[96:111], v[196:199], v[216:219], v[96:111]
	s_waitcnt lgkmcnt(8)
	v_mfma_f32_32x32x16_bf16 v[80:95], v[200:203], v[216:219], v[80:95]
	s_waitcnt lgkmcnt(7)
	v_mfma_f32_32x32x16_bf16 v[64:79], v[204:207], v[216:219], v[64:79]
	s_waitcnt lgkmcnt(6)
	v_mfma_f32_32x32x16_bf16 v[48:63], v[192:195], v[220:223], v[48:63]
	v_mfma_f32_32x32x16_bf16 v[32:47], v[196:199], v[220:223], v[32:47]
	v_mfma_f32_32x32x16_bf16 v[16:31], v[200:203], v[220:223], v[16:31]
	v_mfma_f32_32x32x16_bf16 v[0:15], v[204:207], v[220:223], v[0:15]
	s_waitcnt lgkmcnt(4)
	v_mfma_f32_32x32x16_bf16 v[112:127], v[224:227], v[240:243], v[112:127]
	s_waitcnt lgkmcnt(3)
	v_mfma_f32_32x32x16_bf16 v[96:111], v[228:231], v[240:243], v[96:111]
	s_waitcnt lgkmcnt(2)
	v_mfma_f32_32x32x16_bf16 v[80:95], v[232:235], v[240:243], v[80:95]
	s_waitcnt lgkmcnt(1)
	v_mfma_f32_32x32x16_bf16 v[64:79], v[236:239], v[240:243], v[64:79]
	s_waitcnt lgkmcnt(0)
	v_mfma_f32_32x32x16_bf16 v[48:63], v[224:227], v[244:247], v[48:63]
	v_mfma_f32_32x32x16_bf16 v[32:47], v[228:231], v[244:247], v[32:47]
	v_mfma_f32_32x32x16_bf16 v[16:31], v[232:235], v[244:247], v[16:31]
	v_mfma_f32_32x32x16_bf16 v[0:15], v[236:239], v[244:247], v[0:15]
	s_waitcnt vmcnt(0)
	s_and_b32 s9, s8, 15
	s_cmp_lg_u32 s9, 15
	s_cbranch_scc1 .LBB0_1292
	s_lshl_b32 s8, s8, 1
	s_and_b32 s8, s8, 0x7fffffe0
	s_add_i32 s8, s8, s33
	s_lshr_b32 s8, s8, 3
	s_and_b32 s9, s8, 4
	s_or_b32 s9, s9, s47
	s_and_b32 s8, s8, 0xfffff8
	s_lshl_b32 s28, s9, 8
	s_or_b32 s8, s8, s74
	v_lshl_add_u64 v[136:137], v[134:135], 0, s[28:29]
	s_lshl_b32 s8, s8, 8
	v_lshlrev_b64 v[136:137], 13, v[136:137]
	v_or_b32_e32 v128, s8, v141
	v_lshl_add_u64 v[136:137], s[58:59], 0, v[136:137]
	v_cvt_pk_bf16_f32 v112, v112, v113
	v_cvt_pk_bf16_f32 v113, v114, v115
	v_cvt_pk_bf16_f32 v114, v116, v117
	v_cvt_pk_bf16_f32 v115, v118, v119
	s_cmp_lt_u32 s8, 2.0
	v_permlane32_swap_b32_e32 v112, v114
	s_cselect_b64 s[24:25], -1, 0
	s_cmp_gt_u32 s8, 0x3fffffff
	v_permlane32_swap_b32_e32 v113, v115
	s_cbranch_scc1 .LBB0_1296
	v_lshl_add_u64 v[116:117], v[128:129], 1, v[136:137]
	global_store_dwordx4 v[116:117], v[112:115], off
